# SGU item de-serialised: LN-stats row loads, per-token loads, w_spatial loads and ZU/bias loads each issued as one batch (was one round trip per load); stacked on per-XCC barrier
# speedup vs baseline: 1.0085x; 1.0056x over previous
; #define LAS __attribute__((address_space(3)))
; __device__ __forceinline__ float bf_lo(unsigned v) { return __uint_as_float(v << 16); }
; __device__ __forceinline__ float bf_hi(unsigned v) { return __uint_as_float(v & 0xffff0000u); }
; __device__ __forceinline__ int otid(int wv) { int l; asm volatile("v_mbcnt_lo_u32_b32 %0, -1, 0\n\tv_mbcnt_hi_u32_b32 %0, -1, %0" : "=v"(l)); return wv * 64 + l; }
; __device__ __forceinline__ void sgu_item(int it, const bf16_t* GV, const bf16_t* ZU, const float* sg_, const float* sb_, const float* wsp, const float* bsp, bf16_t* CAT, unsigned char* lds, const int wv) {
;     const int tid = otid(wv), wid = __builtin_amdgcn_readfirstlane(tid >> 6), lane = tid & 63;
;     const int chunk = it >> 3, g = it & 7, tok0 = chunk * 128;
;     LAS unsigned char* ZT = (LAS unsigned char*)lds;
;     __syncthreads();
;     {
;         float mean[16], rstd[16];
; #pragma unroll
;         for (int i = 0; i < 16; ++i) { const bf16_t* row = GV + (size_t)(tok0 + 16 * wid + i) * 1024;
;             const u32x4 a = *(const u32x4*)(row + 8 * lane), c = *(const u32x4*)(row + 512 + 8 * lane);
;             float v[16];
; #pragma unroll
;             for (int k = 0; k < 4; ++k) { v[2 * k] = bf_lo(a[k]); v[2 * k + 1] = bf_hi(a[k]); v[8 + 2 * k] = bf_lo(c[k]); v[8 + 2 * k + 1] = bf_hi(c[k]); }
;             float s = 0.f;
; #pragma unroll
;             for (int k = 0; k < 16; ++k) s += v[k];
;             const float mu = wave_sum(s) * (1.0f / 1024.0f); float q = 0.f;
; #pragma unroll
;             for (int k = 0; k < 16; ++k) { const float d = v[k] - mu; q += d * d; }
;             mean[i] = mu; rstd[i] = 1.0f / sqrtf(wave_sum(q) * (1.0f / 1024.0f) + EPS); }
.LBB0_288:
	v_mbcnt_lo_u32_b32 v16, -1, 0
	v_mbcnt_hi_u32_b32 v16, -1, v16
	s_waitcnt vmcnt(0)
	v_add_u32_e32 v0, s3, v16
	s_barrier
	v_readfirstlane_b32 s1, v0
	s_ashr_i32 s9, s1, 6
	s_and_b32 s1, s92, 0xffffff8
	s_add_i32 s1, s9, s1
	s_lshl_b32 s22, s1, 4
	s_ashr_i32 s23, s22, 31
	s_lshl_b64 s[16:17], s[22:23], 11
	v_and_b32_e32 v0, 63, v16
	s_add_u32 s4, s6, s16
	s_addc_u32 s5, s7, s17
	v_lshlrev_b32_e32 v3, 4, v0
	s_mov_b64 s[98:99], s[4:5]
	global_load_dwordx4 v[64:67], v3, s[98:99]
	global_load_dwordx4 v[68:71], v3, s[98:99] offset:1024
	global_load_dwordx4 v[72:75], v3, s[98:99] offset:2048
	global_load_dwordx4 v[76:79], v3, s[98:99] offset:3072
	s_add_u32 s98, s98, 0x1000
	s_addc_u32 s99, s99, 0
	global_load_dwordx4 v[80:83], v3, s[98:99]
	global_load_dwordx4 v[84:87], v3, s[98:99] offset:1024
	global_load_dwordx4 v[88:91], v3, s[98:99] offset:2048
	global_load_dwordx4 v[92:95], v3, s[98:99] offset:3072
	s_add_u32 s98, s98, 0x1000
	s_addc_u32 s99, s99, 0
	global_load_dwordx4 v[96:99], v3, s[98:99]
	global_load_dwordx4 v[100:103], v3, s[98:99] offset:1024
	global_load_dwordx4 v[104:107], v3, s[98:99] offset:2048
	global_load_dwordx4 v[108:111], v3, s[98:99] offset:3072
	s_add_u32 s98, s98, 0x1000
	s_addc_u32 s99, s99, 0
	global_load_dwordx4 v[112:115], v3, s[98:99]
	global_load_dwordx4 v[116:119], v3, s[98:99] offset:1024
	global_load_dwordx4 v[120:123], v3, s[98:99] offset:2048
	global_load_dwordx4 v[124:127], v3, s[98:99] offset:3072
	s_add_u32 s98, s98, 0x1000
	s_addc_u32 s99, s99, 0
	global_load_dwordx4 v[128:131], v3, s[98:99]
	global_load_dwordx4 v[132:135], v3, s[98:99] offset:1024
	global_load_dwordx4 v[136:139], v3, s[98:99] offset:2048
	global_load_dwordx4 v[140:143], v3, s[98:99] offset:3072
	s_add_u32 s98, s98, 0x1000
	s_addc_u32 s99, s99, 0
	global_load_dwordx4 v[144:147], v3, s[98:99]
	global_load_dwordx4 v[148:151], v3, s[98:99] offset:1024
	global_load_dwordx4 v[152:155], v3, s[98:99] offset:2048
	global_load_dwordx4 v[156:159], v3, s[98:99] offset:3072
	s_add_u32 s98, s98, 0x1000
	s_addc_u32 s99, s99, 0
	global_load_dwordx4 v[160:163], v3, s[98:99]
	global_load_dwordx4 v[164:167], v3, s[98:99] offset:1024
	global_load_dwordx4 v[168:171], v3, s[98:99] offset:2048
	global_load_dwordx4 v[172:175], v3, s[98:99] offset:3072
	s_add_u32 s98, s98, 0x1000
	s_addc_u32 s99, s99, 0
	global_load_dwordx4 v[176:179], v3, s[98:99]
	global_load_dwordx4 v[180:183], v3, s[98:99] offset:1024
	global_load_dwordx4 v[184:187], v3, s[98:99] offset:2048
	global_load_dwordx4 v[188:191], v3, s[98:99] offset:3072
	s_waitcnt vmcnt(30)
	v_mov_b32_e32 v4, v64
	v_mov_b32_e32 v5, v65
	v_mov_b32_e32 v6, v66
	v_mov_b32_e32 v7, v67
	v_mov_b32_e32 v8, v68
	v_mov_b32_e32 v9, v69
	v_mov_b32_e32 v10, v70
	v_mov_b32_e32 v11, v71
	v_lshlrev_b32_e32 v2, 16, v4
	v_and_b32_e32 v4, 0xffff0000, v4
	v_add_f32_e32 v1, 0, v2
	v_lshlrev_b32_e32 v13, 16, v5
	v_add_f32_e32 v1, v1, v4
	v_and_b32_e32 v5, 0xffff0000, v5
	v_add_f32_e32 v1, v1, v13
	v_lshlrev_b32_e32 v15, 16, v6
	v_add_f32_e32 v1, v1, v5
	v_and_b32_e32 v6, 0xffff0000, v6
	v_add_f32_e32 v1, v1, v15
	v_lshlrev_b32_e32 v18, 16, v7
	v_add_f32_e32 v1, v1, v6
	v_and_b32_e32 v7, 0xffff0000, v7
	v_add_f32_e32 v1, v1, v18
	v_lshlrev_b32_e32 v12, 16, v8
	v_add_f32_e32 v1, v1, v7
	v_and_b32_e32 v8, 0xffff0000, v8
	v_add_f32_e32 v1, v1, v12
	v_lshlrev_b32_e32 v14, 16, v9
	v_add_f32_e32 v1, v1, v8
	v_and_b32_e32 v9, 0xffff0000, v9
	v_add_f32_e32 v1, v1, v14
	v_lshlrev_b32_e32 v17, 16, v10
	v_add_f32_e32 v1, v1, v9
	v_and_b32_e32 v10, 0xffff0000, v10
	v_add_f32_e32 v1, v1, v17
	v_lshlrev_b32_e32 v19, 16, v11
	v_add_f32_e32 v1, v1, v10
	v_and_b32_e32 v11, 0xffff0000, v11
	v_add_f32_e32 v1, v1, v19
	v_add_f32_e32 v1, v1, v11
	s_nop 1
	v_add_f32_dpp v1, v1, v1 quad_perm:[1,0,3,2] row_mask:0xf bank_mask:0xf bound_ctrl:1
	s_nop 1
	v_add_f32_dpp v1, v1, v1 quad_perm:[2,3,0,1] row_mask:0xf bank_mask:0xf bound_ctrl:1
	s_nop 1
	v_add_f32_dpp v1, v1, v1 row_half_mirror row_mask:0xf bank_mask:0xf bound_ctrl:1
	s_nop 1
	v_add_f32_dpp v1, v1, v1 row_mirror row_mask:0xf bank_mask:0xf bound_ctrl:1
	ds_swizzle_b32 v20, v1 offset:swizzle(SWAP,16)
	s_waitcnt lgkmcnt(0)
	v_add_f32_e32 v1, v1, v20
	v_mov_b32_e32 v20, v1
	s_nop 1
	v_permlane32_swap_b32_e32 v1, v20
	v_add_f32_e32 v1, v1, v20
	v_fmac_f32_e32 v4, 0xba800000, v1
	v_fmac_f32_e32 v2, 0xba800000, v1
	v_mul_f32_e32 v4, v4, v4
	v_fmac_f32_e32 v4, v2, v2
	v_fmac_f32_e32 v13, 0xba800000, v1
	v_fmac_f32_e32 v4, v13, v13
	v_fmac_f32_e32 v5, 0xba800000, v1
	v_fmac_f32_e32 v4, v5, v5
	v_fmac_f32_e32 v15, 0xba800000, v1
	v_fmac_f32_e32 v4, v15, v15
	v_fmac_f32_e32 v6, 0xba800000, v1
	v_fmac_f32_e32 v4, v6, v6
	v_fmac_f32_e32 v18, 0xba800000, v1
	v_fmac_f32_e32 v4, v18, v18
	v_fmac_f32_e32 v7, 0xba800000, v1
	v_fmac_f32_e32 v4, v7, v7
	v_fmac_f32_e32 v12, 0xba800000, v1
	v_fmac_f32_e32 v4, v12, v12
	v_fmac_f32_e32 v8, 0xba800000, v1
	v_fmac_f32_e32 v4, v8, v8
	v_fmac_f32_e32 v14, 0xba800000, v1
	v_fmac_f32_e32 v4, v14, v14
	v_fmac_f32_e32 v9, 0xba800000, v1
	v_fmac_f32_e32 v4, v9, v9
	v_fmac_f32_e32 v17, 0xba800000, v1
	v_fmac_f32_e32 v4, v17, v17
	v_fmac_f32_e32 v10, 0xba800000, v1
	v_fmac_f32_e32 v4, v10, v10
	v_fmac_f32_e32 v19, 0xba800000, v1
	v_fmac_f32_e32 v4, v19, v19
	v_fmac_f32_e32 v11, 0xba800000, v1
	v_fmac_f32_e32 v4, v11, v11
	s_nop 1
	v_add_f32_dpp v2, v4, v4 quad_perm:[1,0,3,2] row_mask:0xf bank_mask:0xf bound_ctrl:1
	s_nop 1
	v_add_f32_dpp v2, v2, v2 quad_perm:[2,3,0,1] row_mask:0xf bank_mask:0xf bound_ctrl:1
	s_nop 1
	v_add_f32_dpp v2, v2, v2 row_half_mirror row_mask:0xf bank_mask:0xf bound_ctrl:1
	s_nop 1
	v_add_f32_dpp v2, v2, v2 row_mirror row_mask:0xf bank_mask:0xf bound_ctrl:1
	ds_swizzle_b32 v4, v2 offset:swizzle(SWAP,16)
	s_waitcnt lgkmcnt(0)
; __device__ __forceinline__ float bf_lo(unsigned v) { return __uint_as_float(v << 16); }
; __device__ __forceinline__ float bf_hi(unsigned v) { return __uint_as_float(v & 0xffff0000u); }
; __device__ __forceinline__ void sgu_item(int it, const bf16_t* GV, const bf16_t* ZU, const float* sg_, const float* sb_, const float* wsp, const float* bsp, bf16_t* CAT, unsigned char* lds, const int wv) {
;     ...
;         for (int i = 0; i < 16; ++i) { const bf16_t* row = GV + (size_t)(tok0 + 16 * wid + i) * 1024;
;             const u32x4 a = *(const u32x4*)(row + 8 * lane), c = *(const u32x4*)(row + 512 + 8 * lane);
;             float v[16];
; #pragma unroll
;             for (int k = 0; k < 4; ++k) { v[2 * k] = bf_lo(a[k]); v[2 * k + 1] = bf_hi(a[k]); v[8 + 2 * k] = bf_lo(c[k]); v[8 + 2 * k + 1] = bf_hi(c[k]); }
;             float s = 0.f;
; #pragma unroll
;             for (int k = 0; k < 16; ++k) s += v[k];
;             const float mu = wave_sum(s) * (1.0f / 1024.0f); float q = 0.f;
; #pragma unroll
;             for (int k = 0; k < 16; ++k) { const float d = v[k] - mu; q += d * d; }
;             mean[i] = mu; rstd[i] = 1.0f / sqrtf(wave_sum(q) * (1.0f / 1024.0f) + EPS); }
	v_add_f32_e32 v2, v2, v4
	v_mov_b32_e32 v4, v2
	s_nop 1
	v_permlane32_swap_b32_e32 v2, v4
	v_add_f32_e32 v2, v2, v4
	v_fmamk_f32 v2, v2, 0x3a800000, v244
	v_cmp_gt_f32_e32 vcc, s81, v2
	v_mul_f32_e32 v4, 0x4f800000, v2
	s_nop 0
	v_cndmask_b32_e32 v2, v2, v4, vcc
	v_sqrt_f32_e32 v4, v2
	s_nop 0
	v_add_u32_e32 v5, -1, v4
	v_fma_f32 v6, -v5, v4, v2
	v_cmp_ge_f32_e64 s[4:5], 0, v6
	v_add_u32_e32 v6, 1, v4
	s_nop 0
	v_cndmask_b32_e64 v5, v4, v5, s[4:5]
	v_fma_f32 v4, -v6, v4, v2
	v_cmp_lt_f32_e64 s[4:5], 0, v4
	s_nop 1
	v_cndmask_b32_e64 v4, v5, v6, s[4:5]
	v_mul_f32_e32 v5, 0x37800000, v4
	v_cndmask_b32_e32 v4, v4, v5, vcc
	v_cmp_class_f32_e32 vcc, v2, v245
	s_nop 1
	v_cndmask_b32_e32 v2, v4, v2, vcc
	v_div_scale_f32 v4, s[4:5], v2, v2, 1.0
	v_rcp_f32_e32 v5, v4
	s_or_b32 s4, s22, 1
	s_ashr_i32 s5, s4, 31
	s_lshl_b64 s[20:21], s[4:5], 11
	v_fma_f32 v6, -v4, v5, 1.0
	v_fmac_f32_e32 v5, v6, v5
	v_div_scale_f32 v6, vcc, 1.0, v2, 1.0
	v_mul_f32_e32 v7, v6, v5
	v_fma_f32 v8, -v4, v7, v6
	v_fmac_f32_e32 v7, v8, v5
	v_fma_f32 v4, -v4, v7, v6
	s_add_u32 s4, s6, s20
	v_div_fmas_f32 v4, v4, v5, v7
	s_addc_u32 s5, s7, s21
	v_div_fixup_f32 v2, v4, v2, 1.0
	s_waitcnt vmcnt(28)
	v_mov_b32_e32 v4, v72
	v_mov_b32_e32 v5, v73
	v_mov_b32_e32 v6, v74
	v_mov_b32_e32 v7, v75
	v_mov_b32_e32 v8, v76
	v_mov_b32_e32 v9, v77
	v_mov_b32_e32 v10, v78
	v_mov_b32_e32 v11, v79
	v_lshlrev_b32_e32 v12, 16, v4
	v_and_b32_e32 v13, 0xffff0000, v4
	v_add_f32_e32 v4, 0, v12
	v_lshlrev_b32_e32 v15, 16, v5
	v_add_f32_e32 v4, v4, v13
	v_and_b32_e32 v5, 0xffff0000, v5
	v_add_f32_e32 v4, v4, v15
	v_lshlrev_b32_e32 v18, 16, v6
	v_add_f32_e32 v4, v4, v5
	v_and_b32_e32 v6, 0xffff0000, v6
	v_add_f32_e32 v4, v4, v18
	v_lshlrev_b32_e32 v20, 16, v7
	v_add_f32_e32 v4, v4, v6
	v_and_b32_e32 v7, 0xffff0000, v7
	v_add_f32_e32 v4, v4, v20
	v_lshlrev_b32_e32 v14, 16, v8
	v_add_f32_e32 v4, v4, v7
	v_and_b32_e32 v8, 0xffff0000, v8
	v_add_f32_e32 v4, v4, v14
	v_lshlrev_b32_e32 v17, 16, v9
	v_add_f32_e32 v4, v4, v8
	v_and_b32_e32 v9, 0xffff0000, v9
	v_add_f32_e32 v4, v4, v17
	v_lshlrev_b32_e32 v19, 16, v10
	v_add_f32_e32 v4, v4, v9
	v_and_b32_e32 v10, 0xffff0000, v10
	v_add_f32_e32 v4, v4, v19
	v_lshlrev_b32_e32 v21, 16, v11
	v_add_f32_e32 v4, v4, v10
	v_and_b32_e32 v11, 0xffff0000, v11
	v_add_f32_e32 v4, v4, v21
	v_add_f32_e32 v4, v4, v11
	s_nop 1
	v_add_f32_dpp v4, v4, v4 quad_perm:[1,0,3,2] row_mask:0xf bank_mask:0xf bound_ctrl:1
	s_nop 1
	v_add_f32_dpp v4, v4, v4 quad_perm:[2,3,0,1] row_mask:0xf bank_mask:0xf bound_ctrl:1
	s_nop 1
	v_add_f32_dpp v4, v4, v4 row_half_mirror row_mask:0xf bank_mask:0xf bound_ctrl:1
	s_nop 1
	v_add_f32_dpp v4, v4, v4 row_mirror row_mask:0xf bank_mask:0xf bound_ctrl:1
	ds_swizzle_b32 v22, v4 offset:swizzle(SWAP,16)
	s_waitcnt lgkmcnt(0)
	v_add_f32_e32 v4, v4, v22
	v_mov_b32_e32 v22, v4
	s_nop 1
	v_permlane32_swap_b32_e32 v4, v22
	v_add_f32_e32 v4, v4, v22
	v_fmac_f32_e32 v13, 0xba800000, v4
	v_fmac_f32_e32 v12, 0xba800000, v4
	v_mul_f32_e32 v13, v13, v13
	v_fmac_f32_e32 v13, v12, v12
	v_fmac_f32_e32 v15, 0xba800000, v4
	v_fmac_f32_e32 v13, v15, v15
	v_fmac_f32_e32 v5, 0xba800000, v4
	v_fmac_f32_e32 v13, v5, v5
	v_fmac_f32_e32 v18, 0xba800000, v4
	v_fmac_f32_e32 v13, v18, v18
	v_fmac_f32_e32 v6, 0xba800000, v4
	v_fmac_f32_e32 v13, v6, v6
	v_fmac_f32_e32 v20, 0xba800000, v4
	v_fmac_f32_e32 v13, v20, v20
	v_fmac_f32_e32 v7, 0xba800000, v4
	v_fmac_f32_e32 v13, v7, v7
	v_fmac_f32_e32 v14, 0xba800000, v4
	v_fmac_f32_e32 v13, v14, v14
	v_fmac_f32_e32 v8, 0xba800000, v4
	v_fmac_f32_e32 v13, v8, v8
	v_fmac_f32_e32 v17, 0xba800000, v4
	v_fmac_f32_e32 v13, v17, v17
	v_fmac_f32_e32 v9, 0xba800000, v4
	v_fmac_f32_e32 v13, v9, v9
	v_fmac_f32_e32 v19, 0xba800000, v4
	v_fmac_f32_e32 v13, v19, v19
	v_fmac_f32_e32 v10, 0xba800000, v4
	v_fmac_f32_e32 v13, v10, v10
	v_fmac_f32_e32 v21, 0xba800000, v4
	v_fmac_f32_e32 v13, v21, v21
	v_fmac_f32_e32 v11, 0xba800000, v4
	v_fmac_f32_e32 v13, v11, v11
	s_nop 1
	v_add_f32_dpp v5, v13, v13 quad_perm:[1,0,3,2] row_mask:0xf bank_mask:0xf bound_ctrl:1
	s_nop 1
	v_add_f32_dpp v5, v5, v5 quad_perm:[2,3,0,1] row_mask:0xf bank_mask:0xf bound_ctrl:1
	s_nop 1
	v_add_f32_dpp v5, v5, v5 row_half_mirror row_mask:0xf bank_mask:0xf bound_ctrl:1
	s_nop 1
	v_add_f32_dpp v5, v5, v5 row_mirror row_mask:0xf bank_mask:0xf bound_ctrl:1
	ds_swizzle_b32 v6, v5 offset:swizzle(SWAP,16)
	s_waitcnt lgkmcnt(0)
	v_add_f32_e32 v5, v5, v6
	v_mov_b32_e32 v6, v5
	s_nop 1
	v_permlane32_swap_b32_e32 v5, v6
	v_add_f32_e32 v5, v5, v6
	v_fmamk_f32 v5, v5, 0x3a800000, v244
	v_cmp_gt_f32_e32 vcc, s81, v5
	v_mul_f32_e32 v6, 0x4f800000, v5
	s_nop 0
	v_cndmask_b32_e32 v5, v5, v6, vcc
	v_sqrt_f32_e32 v6, v5
	s_nop 0
	v_add_u32_e32 v7, -1, v6
	v_fma_f32 v8, -v7, v6, v5
	v_cmp_ge_f32_e64 s[4:5], 0, v8
	v_add_u32_e32 v8, 1, v6
	s_nop 0
	v_cndmask_b32_e64 v7, v6, v7, s[4:5]
	v_fma_f32 v6, -v8, v6, v5
	v_cmp_lt_f32_e64 s[4:5], 0, v6
	s_nop 1
	v_cndmask_b32_e64 v6, v7, v8, s[4:5]
	v_mul_f32_e32 v7, 0x37800000, v6
	v_cndmask_b32_e32 v6, v6, v7, vcc
	v_cmp_class_f32_e32 vcc, v5, v245
	s_nop 1
	v_cndmask_b32_e32 v5, v6, v5, vcc
	v_div_scale_f32 v6, s[4:5], v5, v5, 1.0
	v_rcp_f32_e32 v7, v6
	s_or_b32 s4, s22, 2
	s_ashr_i32 s5, s4, 31
	s_lshl_b64 s[28:29], s[4:5], 11
	v_fma_f32 v8, -v6, v7, 1.0
	v_fmac_f32_e32 v7, v8, v7
	v_div_scale_f32 v8, vcc, 1.0, v5, 1.0
	v_mul_f32_e32 v9, v8, v7
	v_fma_f32 v10, -v6, v9, v8
	v_fmac_f32_e32 v9, v10, v7
	v_fma_f32 v6, -v6, v9, v8
	s_add_u32 s4, s6, s28
	v_div_fmas_f32 v6, v6, v7, v9
	s_addc_u32 s5, s7, s29
	v_div_fixup_f32 v5, v6, v5, 1.0
	s_waitcnt vmcnt(26)
; __device__ __forceinline__ float bf_lo(unsigned v) { return __uint_as_float(v << 16); }
; __device__ __forceinline__ float bf_hi(unsigned v) { return __uint_as_float(v & 0xffff0000u); }
; __device__ __forceinline__ void sgu_item(int it, const bf16_t* GV, const bf16_t* ZU, const float* sg_, const float* sb_, const float* wsp, const float* bsp, bf16_t* CAT, unsigned char* lds, const int wv) {
;     ...
;         for (int i = 0; i < 16; ++i) { const bf16_t* row = GV + (size_t)(tok0 + 16 * wid + i) * 1024;
;             const u32x4 a = *(const u32x4*)(row + 8 * lane), c = *(const u32x4*)(row + 512 + 8 * lane);
;             float v[16];
; #pragma unroll
;             for (int k = 0; k < 4; ++k) { v[2 * k] = bf_lo(a[k]); v[2 * k + 1] = bf_hi(a[k]); v[8 + 2 * k] = bf_lo(c[k]); v[8 + 2 * k + 1] = bf_hi(c[k]); }
;             float s = 0.f;
; #pragma unroll
;             for (int k = 0; k < 16; ++k) s += v[k];
;             const float mu = wave_sum(s) * (1.0f / 1024.0f); float q = 0.f;
; #pragma unroll
;             for (int k = 0; k < 16; ++k) { const float d = v[k] - mu; q += d * d; }
;             mean[i] = mu; rstd[i] = 1.0f / sqrtf(wave_sum(q) * (1.0f / 1024.0f) + EPS); }
	v_mov_b32_e32 v6, v80
	v_mov_b32_e32 v7, v81
	v_mov_b32_e32 v8, v82
	v_mov_b32_e32 v9, v83
	v_mov_b32_e32 v10, v84
	v_mov_b32_e32 v11, v85
	v_mov_b32_e32 v12, v86
	v_mov_b32_e32 v13, v87
	v_lshlrev_b32_e32 v14, 16, v6
	v_and_b32_e32 v15, 0xffff0000, v6
	v_add_f32_e32 v6, 0, v14
	v_lshlrev_b32_e32 v18, 16, v7
	v_add_f32_e32 v6, v6, v15
	v_and_b32_e32 v7, 0xffff0000, v7
	v_add_f32_e32 v6, v6, v18
	v_lshlrev_b32_e32 v20, 16, v8
	v_add_f32_e32 v6, v6, v7
	v_and_b32_e32 v8, 0xffff0000, v8
	v_add_f32_e32 v6, v6, v20
	v_lshlrev_b32_e32 v22, 16, v9
	v_add_f32_e32 v6, v6, v8
	v_and_b32_e32 v9, 0xffff0000, v9
	v_add_f32_e32 v6, v6, v22
	v_lshlrev_b32_e32 v17, 16, v10
	v_add_f32_e32 v6, v6, v9
	v_and_b32_e32 v10, 0xffff0000, v10
	v_add_f32_e32 v6, v6, v17
	v_lshlrev_b32_e32 v19, 16, v11
	v_add_f32_e32 v6, v6, v10
	v_and_b32_e32 v11, 0xffff0000, v11
	v_add_f32_e32 v6, v6, v19
	v_lshlrev_b32_e32 v21, 16, v12
	v_add_f32_e32 v6, v6, v11
	v_and_b32_e32 v12, 0xffff0000, v12
	v_add_f32_e32 v6, v6, v21
	v_lshlrev_b32_e32 v23, 16, v13
	v_add_f32_e32 v6, v6, v12
	v_and_b32_e32 v13, 0xffff0000, v13
	v_add_f32_e32 v6, v6, v23
	v_add_f32_e32 v6, v6, v13
	s_nop 1
	v_add_f32_dpp v6, v6, v6 quad_perm:[1,0,3,2] row_mask:0xf bank_mask:0xf bound_ctrl:1
	s_nop 1
	v_add_f32_dpp v6, v6, v6 quad_perm:[2,3,0,1] row_mask:0xf bank_mask:0xf bound_ctrl:1
	s_nop 1
	v_add_f32_dpp v6, v6, v6 row_half_mirror row_mask:0xf bank_mask:0xf bound_ctrl:1
	s_nop 1
	v_add_f32_dpp v6, v6, v6 row_mirror row_mask:0xf bank_mask:0xf bound_ctrl:1
	ds_swizzle_b32 v24, v6 offset:swizzle(SWAP,16)
	s_waitcnt lgkmcnt(0)
	v_add_f32_e32 v6, v6, v24
	v_mov_b32_e32 v24, v6
	s_nop 1
	v_permlane32_swap_b32_e32 v6, v24
	v_add_f32_e32 v6, v6, v24
	v_fmac_f32_e32 v15, 0xba800000, v6
	v_fmac_f32_e32 v14, 0xba800000, v6
	v_mul_f32_e32 v15, v15, v15
	v_fmac_f32_e32 v15, v14, v14
	v_fmac_f32_e32 v18, 0xba800000, v6
	v_fmac_f32_e32 v15, v18, v18
	v_fmac_f32_e32 v7, 0xba800000, v6
	v_fmac_f32_e32 v15, v7, v7
	v_fmac_f32_e32 v20, 0xba800000, v6
	v_fmac_f32_e32 v15, v20, v20
	v_fmac_f32_e32 v8, 0xba800000, v6
	v_fmac_f32_e32 v15, v8, v8
	v_fmac_f32_e32 v22, 0xba800000, v6
	v_fmac_f32_e32 v15, v22, v22
	v_fmac_f32_e32 v9, 0xba800000, v6
	v_fmac_f32_e32 v15, v9, v9
	v_fmac_f32_e32 v17, 0xba800000, v6
	v_fmac_f32_e32 v15, v17, v17
	v_fmac_f32_e32 v10, 0xba800000, v6
	v_fmac_f32_e32 v15, v10, v10
	v_fmac_f32_e32 v19, 0xba800000, v6
	v_fmac_f32_e32 v15, v19, v19
	v_fmac_f32_e32 v11, 0xba800000, v6
	v_fmac_f32_e32 v15, v11, v11
	v_fmac_f32_e32 v21, 0xba800000, v6
	v_fmac_f32_e32 v15, v21, v21
	v_fmac_f32_e32 v12, 0xba800000, v6
	v_fmac_f32_e32 v15, v12, v12
	v_fmac_f32_e32 v23, 0xba800000, v6
	v_fmac_f32_e32 v15, v23, v23
	v_fmac_f32_e32 v13, 0xba800000, v6
	v_fmac_f32_e32 v15, v13, v13
	s_nop 1
	v_add_f32_dpp v7, v15, v15 quad_perm:[1,0,3,2] row_mask:0xf bank_mask:0xf bound_ctrl:1
	s_nop 1
	v_add_f32_dpp v7, v7, v7 quad_perm:[2,3,0,1] row_mask:0xf bank_mask:0xf bound_ctrl:1
	s_nop 1
	v_add_f32_dpp v7, v7, v7 row_half_mirror row_mask:0xf bank_mask:0xf bound_ctrl:1
	s_nop 1
	v_add_f32_dpp v7, v7, v7 row_mirror row_mask:0xf bank_mask:0xf bound_ctrl:1
	ds_swizzle_b32 v8, v7 offset:swizzle(SWAP,16)
	s_waitcnt lgkmcnt(0)
	v_add_f32_e32 v7, v7, v8
	v_mov_b32_e32 v8, v7
	s_nop 1
	v_permlane32_swap_b32_e32 v7, v8
	v_add_f32_e32 v7, v7, v8
	v_fmamk_f32 v7, v7, 0x3a800000, v244
	v_cmp_gt_f32_e32 vcc, s81, v7
	v_mul_f32_e32 v8, 0x4f800000, v7
	s_nop 0
	v_cndmask_b32_e32 v7, v7, v8, vcc
	v_sqrt_f32_e32 v8, v7
	s_nop 0
	v_add_u32_e32 v9, -1, v8
	v_fma_f32 v10, -v9, v8, v7
	v_cmp_ge_f32_e64 s[4:5], 0, v10
	v_add_u32_e32 v10, 1, v8
	s_nop 0
	v_cndmask_b32_e64 v9, v8, v9, s[4:5]
	v_fma_f32 v8, -v10, v8, v7
	v_cmp_lt_f32_e64 s[4:5], 0, v8
	s_nop 1
	v_cndmask_b32_e64 v8, v9, v10, s[4:5]
	v_mul_f32_e32 v9, 0x37800000, v8
	v_cndmask_b32_e32 v8, v8, v9, vcc
	v_cmp_class_f32_e32 vcc, v7, v245
	s_nop 1
	v_cndmask_b32_e32 v7, v8, v7, vcc
	v_div_scale_f32 v8, s[4:5], v7, v7, 1.0
	v_rcp_f32_e32 v9, v8
	s_or_b32 s4, s22, 3
	s_ashr_i32 s5, s4, 31
	s_lshl_b64 s[30:31], s[4:5], 11
	v_fma_f32 v10, -v8, v9, 1.0
	v_fmac_f32_e32 v9, v10, v9
	v_div_scale_f32 v10, vcc, 1.0, v7, 1.0
	v_mul_f32_e32 v11, v10, v9
	v_fma_f32 v12, -v8, v11, v10
	v_fmac_f32_e32 v11, v12, v9
	v_fma_f32 v8, -v8, v11, v10
	s_add_u32 s4, s6, s30
	v_div_fmas_f32 v8, v8, v9, v11
	s_addc_u32 s5, s7, s31
	v_div_fixup_f32 v7, v8, v7, 1.0
	s_waitcnt vmcnt(24)
	v_mov_b32_e32 v8, v88
	v_mov_b32_e32 v9, v89
	v_mov_b32_e32 v10, v90
	v_mov_b32_e32 v11, v91
	v_mov_b32_e32 v12, v92
	v_mov_b32_e32 v13, v93
	v_mov_b32_e32 v14, v94
	v_mov_b32_e32 v15, v95
	v_lshlrev_b32_e32 v17, 16, v8
	v_and_b32_e32 v18, 0xffff0000, v8
	v_add_f32_e32 v8, 0, v17
	v_lshlrev_b32_e32 v20, 16, v9
	v_add_f32_e32 v8, v8, v18
	v_and_b32_e32 v9, 0xffff0000, v9
	v_add_f32_e32 v8, v8, v20
	v_lshlrev_b32_e32 v22, 16, v10
	v_add_f32_e32 v8, v8, v9
	v_and_b32_e32 v10, 0xffff0000, v10
	v_add_f32_e32 v8, v8, v22
	v_lshlrev_b32_e32 v24, 16, v11
	v_add_f32_e32 v8, v8, v10
	v_and_b32_e32 v11, 0xffff0000, v11
	v_add_f32_e32 v8, v8, v24
	v_lshlrev_b32_e32 v19, 16, v12
	v_add_f32_e32 v8, v8, v11
	v_and_b32_e32 v12, 0xffff0000, v12
	v_add_f32_e32 v8, v8, v19
	v_lshlrev_b32_e32 v21, 16, v13
	v_add_f32_e32 v8, v8, v12
	v_and_b32_e32 v13, 0xffff0000, v13
	v_add_f32_e32 v8, v8, v21
	v_lshlrev_b32_e32 v23, 16, v14
	v_add_f32_e32 v8, v8, v13
	v_and_b32_e32 v14, 0xffff0000, v14
	v_add_f32_e32 v8, v8, v23
	v_lshlrev_b32_e32 v25, 16, v15
	v_add_f32_e32 v8, v8, v14
	v_and_b32_e32 v15, 0xffff0000, v15
	v_add_f32_e32 v8, v8, v25
	v_add_f32_e32 v8, v8, v15
	s_nop 1
	v_add_f32_dpp v8, v8, v8 quad_perm:[1,0,3,2] row_mask:0xf bank_mask:0xf bound_ctrl:1
	s_nop 1
	v_add_f32_dpp v8, v8, v8 quad_perm:[2,3,0,1] row_mask:0xf bank_mask:0xf bound_ctrl:1
	s_nop 1
	v_add_f32_dpp v8, v8, v8 row_half_mirror row_mask:0xf bank_mask:0xf bound_ctrl:1
	s_nop 1
	v_add_f32_dpp v8, v8, v8 row_mirror row_mask:0xf bank_mask:0xf bound_ctrl:1
	ds_swizzle_b32 v26, v8 offset:swizzle(SWAP,16)
	s_waitcnt lgkmcnt(0)
; __device__ __forceinline__ float bf_lo(unsigned v) { return __uint_as_float(v << 16); }
; __device__ __forceinline__ float bf_hi(unsigned v) { return __uint_as_float(v & 0xffff0000u); }
; __device__ __forceinline__ void sgu_item(int it, const bf16_t* GV, const bf16_t* ZU, const float* sg_, const float* sb_, const float* wsp, const float* bsp, bf16_t* CAT, unsigned char* lds, const int wv) {
;     ...
;         for (int i = 0; i < 16; ++i) { const bf16_t* row = GV + (size_t)(tok0 + 16 * wid + i) * 1024;
;             const u32x4 a = *(const u32x4*)(row + 8 * lane), c = *(const u32x4*)(row + 512 + 8 * lane);
;             float v[16];
; #pragma unroll
;             for (int k = 0; k < 4; ++k) { v[2 * k] = bf_lo(a[k]); v[2 * k + 1] = bf_hi(a[k]); v[8 + 2 * k] = bf_lo(c[k]); v[8 + 2 * k + 1] = bf_hi(c[k]); }
;             float s = 0.f;
; #pragma unroll
;             for (int k = 0; k < 16; ++k) s += v[k];
;             const float mu = wave_sum(s) * (1.0f / 1024.0f); float q = 0.f;
; #pragma unroll
;             for (int k = 0; k < 16; ++k) { const float d = v[k] - mu; q += d * d; }
;             mean[i] = mu; rstd[i] = 1.0f / sqrtf(wave_sum(q) * (1.0f / 1024.0f) + EPS); }
	v_add_f32_e32 v8, v8, v26
	v_mov_b32_e32 v26, v8
	s_nop 1
	v_permlane32_swap_b32_e32 v8, v26
	v_add_f32_e32 v8, v8, v26
	v_fmac_f32_e32 v18, 0xba800000, v8
	v_fmac_f32_e32 v17, 0xba800000, v8
	v_mul_f32_e32 v18, v18, v18
	v_fmac_f32_e32 v18, v17, v17
	v_fmac_f32_e32 v20, 0xba800000, v8
	v_fmac_f32_e32 v18, v20, v20
	v_fmac_f32_e32 v9, 0xba800000, v8
	v_fmac_f32_e32 v18, v9, v9
	v_fmac_f32_e32 v22, 0xba800000, v8
	v_fmac_f32_e32 v18, v22, v22
	v_fmac_f32_e32 v10, 0xba800000, v8
	v_fmac_f32_e32 v18, v10, v10
	v_fmac_f32_e32 v24, 0xba800000, v8
	v_fmac_f32_e32 v18, v24, v24
	v_fmac_f32_e32 v11, 0xba800000, v8
	v_fmac_f32_e32 v18, v11, v11
	v_fmac_f32_e32 v19, 0xba800000, v8
	v_fmac_f32_e32 v18, v19, v19
	v_fmac_f32_e32 v12, 0xba800000, v8
	v_fmac_f32_e32 v18, v12, v12
	v_fmac_f32_e32 v21, 0xba800000, v8
	v_fmac_f32_e32 v18, v21, v21
	v_fmac_f32_e32 v13, 0xba800000, v8
	v_fmac_f32_e32 v18, v13, v13
	v_fmac_f32_e32 v23, 0xba800000, v8
	v_fmac_f32_e32 v18, v23, v23
	v_fmac_f32_e32 v14, 0xba800000, v8
	v_fmac_f32_e32 v18, v14, v14
	v_fmac_f32_e32 v25, 0xba800000, v8
	v_fmac_f32_e32 v18, v25, v25
	v_fmac_f32_e32 v15, 0xba800000, v8
	v_fmac_f32_e32 v18, v15, v15
	s_nop 1
	v_add_f32_dpp v9, v18, v18 quad_perm:[1,0,3,2] row_mask:0xf bank_mask:0xf bound_ctrl:1
	s_nop 1
	v_add_f32_dpp v9, v9, v9 quad_perm:[2,3,0,1] row_mask:0xf bank_mask:0xf bound_ctrl:1
	s_nop 1
	v_add_f32_dpp v9, v9, v9 row_half_mirror row_mask:0xf bank_mask:0xf bound_ctrl:1
	s_nop 1
	v_add_f32_dpp v9, v9, v9 row_mirror row_mask:0xf bank_mask:0xf bound_ctrl:1
	ds_swizzle_b32 v10, v9 offset:swizzle(SWAP,16)
	s_waitcnt lgkmcnt(0)
	v_add_f32_e32 v9, v9, v10
	v_mov_b32_e32 v10, v9
	s_nop 1
	v_permlane32_swap_b32_e32 v9, v10
	v_add_f32_e32 v9, v9, v10
	v_fmamk_f32 v9, v9, 0x3a800000, v244
	v_cmp_gt_f32_e32 vcc, s81, v9
	v_mul_f32_e32 v10, 0x4f800000, v9
	s_nop 0
	v_cndmask_b32_e32 v9, v9, v10, vcc
	v_sqrt_f32_e32 v10, v9
	s_nop 0
	v_add_u32_e32 v11, -1, v10
	v_fma_f32 v12, -v11, v10, v9
	v_cmp_ge_f32_e64 s[4:5], 0, v12
	v_add_u32_e32 v12, 1, v10
	s_nop 0
	v_cndmask_b32_e64 v11, v10, v11, s[4:5]
	v_fma_f32 v10, -v12, v10, v9
	v_cmp_lt_f32_e64 s[4:5], 0, v10
	s_nop 1
	v_cndmask_b32_e64 v10, v11, v12, s[4:5]
	v_mul_f32_e32 v11, 0x37800000, v10
	v_cndmask_b32_e32 v10, v10, v11, vcc
	v_cmp_class_f32_e32 vcc, v9, v245
	s_nop 1
	v_cndmask_b32_e32 v9, v10, v9, vcc
	v_div_scale_f32 v10, s[4:5], v9, v9, 1.0
	v_rcp_f32_e32 v11, v10
	s_or_b32 s4, s22, 4
	s_ashr_i32 s5, s4, 31
	s_lshl_b64 s[34:35], s[4:5], 11
	v_fma_f32 v12, -v10, v11, 1.0
	v_fmac_f32_e32 v11, v12, v11
	v_div_scale_f32 v12, vcc, 1.0, v9, 1.0
	v_mul_f32_e32 v13, v12, v11
	v_fma_f32 v14, -v10, v13, v12
	v_fmac_f32_e32 v13, v14, v11
	v_fma_f32 v10, -v10, v13, v12
	s_add_u32 s4, s6, s34
	v_div_fmas_f32 v10, v10, v11, v13
	s_addc_u32 s5, s7, s35
	v_div_fixup_f32 v9, v10, v9, 1.0
	s_waitcnt vmcnt(22)
	v_mov_b32_e32 v10, v96
	v_mov_b32_e32 v11, v97
	v_mov_b32_e32 v12, v98
	v_mov_b32_e32 v13, v99
	v_mov_b32_e32 v18, v100
	v_mov_b32_e32 v19, v101
	v_mov_b32_e32 v20, v102
	v_mov_b32_e32 v21, v103
	v_lshlrev_b32_e32 v14, 16, v10
	v_and_b32_e32 v15, 0xffff0000, v10
	v_add_f32_e32 v10, 0, v14
	v_lshlrev_b32_e32 v22, 16, v11
	v_add_f32_e32 v10, v10, v15
	v_and_b32_e32 v11, 0xffff0000, v11
	v_add_f32_e32 v10, v10, v22
	v_lshlrev_b32_e32 v24, 16, v12
	v_add_f32_e32 v10, v10, v11
	v_and_b32_e32 v12, 0xffff0000, v12
	v_add_f32_e32 v10, v10, v24
	v_lshlrev_b32_e32 v26, 16, v13
	v_add_f32_e32 v10, v10, v12
	v_and_b32_e32 v13, 0xffff0000, v13
	v_add_f32_e32 v10, v10, v26
	v_lshlrev_b32_e32 v17, 16, v18
	v_add_f32_e32 v10, v10, v13
	v_and_b32_e32 v18, 0xffff0000, v18
	v_add_f32_e32 v10, v10, v17
	v_lshlrev_b32_e32 v23, 16, v19
	v_add_f32_e32 v10, v10, v18
	v_and_b32_e32 v19, 0xffff0000, v19
	v_add_f32_e32 v10, v10, v23
	v_lshlrev_b32_e32 v25, 16, v20
	v_add_f32_e32 v10, v10, v19
	v_and_b32_e32 v20, 0xffff0000, v20
	v_add_f32_e32 v10, v10, v25
	v_lshlrev_b32_e32 v27, 16, v21
	v_add_f32_e32 v10, v10, v20
	v_and_b32_e32 v21, 0xffff0000, v21
	v_add_f32_e32 v10, v10, v27
	v_add_f32_e32 v10, v10, v21
	s_nop 1
	v_add_f32_dpp v10, v10, v10 quad_perm:[1,0,3,2] row_mask:0xf bank_mask:0xf bound_ctrl:1
	s_nop 1
	v_add_f32_dpp v10, v10, v10 quad_perm:[2,3,0,1] row_mask:0xf bank_mask:0xf bound_ctrl:1
	s_nop 1
	v_add_f32_dpp v10, v10, v10 row_half_mirror row_mask:0xf bank_mask:0xf bound_ctrl:1
	s_nop 1
	v_add_f32_dpp v10, v10, v10 row_mirror row_mask:0xf bank_mask:0xf bound_ctrl:1
	ds_swizzle_b32 v28, v10 offset:swizzle(SWAP,16)
	s_waitcnt lgkmcnt(0)
	v_add_f32_e32 v10, v10, v28
	v_mov_b32_e32 v28, v10
	s_nop 1
	v_permlane32_swap_b32_e32 v10, v28
	v_add_f32_e32 v10, v10, v28
	v_fmac_f32_e32 v15, 0xba800000, v10
	v_fmac_f32_e32 v14, 0xba800000, v10
	v_mul_f32_e32 v15, v15, v15
	v_fmac_f32_e32 v15, v14, v14
	v_fmac_f32_e32 v22, 0xba800000, v10
	v_fmac_f32_e32 v15, v22, v22
	v_fmac_f32_e32 v11, 0xba800000, v10
	v_fmac_f32_e32 v15, v11, v11
	v_fmac_f32_e32 v24, 0xba800000, v10
	v_fmac_f32_e32 v15, v24, v24
	v_fmac_f32_e32 v12, 0xba800000, v10
	v_fmac_f32_e32 v15, v12, v12
	v_fmac_f32_e32 v26, 0xba800000, v10
	v_fmac_f32_e32 v15, v26, v26
	v_fmac_f32_e32 v13, 0xba800000, v10
	v_fmac_f32_e32 v15, v13, v13
	v_fmac_f32_e32 v17, 0xba800000, v10
	v_fmac_f32_e32 v15, v17, v17
	v_fmac_f32_e32 v18, 0xba800000, v10
	v_fmac_f32_e32 v15, v18, v18
	v_fmac_f32_e32 v23, 0xba800000, v10
	v_fmac_f32_e32 v15, v23, v23
	v_fmac_f32_e32 v19, 0xba800000, v10
	v_fmac_f32_e32 v15, v19, v19
	v_fmac_f32_e32 v25, 0xba800000, v10
	v_fmac_f32_e32 v15, v25, v25
	v_fmac_f32_e32 v20, 0xba800000, v10
	v_fmac_f32_e32 v15, v20, v20
	v_fmac_f32_e32 v27, 0xba800000, v10
	v_fmac_f32_e32 v15, v27, v27
	v_fmac_f32_e32 v21, 0xba800000, v10
	v_fmac_f32_e32 v15, v21, v21
	s_nop 1
	v_add_f32_dpp v11, v15, v15 quad_perm:[1,0,3,2] row_mask:0xf bank_mask:0xf bound_ctrl:1
	s_nop 1
	v_add_f32_dpp v11, v11, v11 quad_perm:[2,3,0,1] row_mask:0xf bank_mask:0xf bound_ctrl:1
	s_nop 1
	v_add_f32_dpp v11, v11, v11 row_half_mirror row_mask:0xf bank_mask:0xf bound_ctrl:1
	s_nop 1
	v_add_f32_dpp v11, v11, v11 row_mirror row_mask:0xf bank_mask:0xf bound_ctrl:1
	ds_swizzle_b32 v12, v11 offset:swizzle(SWAP,16)
	s_waitcnt lgkmcnt(0)
; __device__ __forceinline__ float bf_lo(unsigned v) { return __uint_as_float(v << 16); }
; __device__ __forceinline__ float bf_hi(unsigned v) { return __uint_as_float(v & 0xffff0000u); }
; __device__ __forceinline__ void sgu_item(int it, const bf16_t* GV, const bf16_t* ZU, const float* sg_, const float* sb_, const float* wsp, const float* bsp, bf16_t* CAT, unsigned char* lds, const int wv) {
;     ...
;         for (int i = 0; i < 16; ++i) { const bf16_t* row = GV + (size_t)(tok0 + 16 * wid + i) * 1024;
;             const u32x4 a = *(const u32x4*)(row + 8 * lane), c = *(const u32x4*)(row + 512 + 8 * lane);
;             float v[16];
; #pragma unroll
;             for (int k = 0; k < 4; ++k) { v[2 * k] = bf_lo(a[k]); v[2 * k + 1] = bf_hi(a[k]); v[8 + 2 * k] = bf_lo(c[k]); v[8 + 2 * k + 1] = bf_hi(c[k]); }
;             float s = 0.f;
; #pragma unroll
;             for (int k = 0; k < 16; ++k) s += v[k];
;             const float mu = wave_sum(s) * (1.0f / 1024.0f); float q = 0.f;
; #pragma unroll
;             for (int k = 0; k < 16; ++k) { const float d = v[k] - mu; q += d * d; }
;             mean[i] = mu; rstd[i] = 1.0f / sqrtf(wave_sum(q) * (1.0f / 1024.0f) + EPS); }
	v_add_f32_e32 v11, v11, v12
	v_mov_b32_e32 v12, v11
	s_nop 1
	v_permlane32_swap_b32_e32 v11, v12
	v_add_f32_e32 v11, v11, v12
	v_fmamk_f32 v11, v11, 0x3a800000, v244
	v_cmp_gt_f32_e32 vcc, s81, v11
	v_mul_f32_e32 v12, 0x4f800000, v11
	s_nop 0
	v_cndmask_b32_e32 v11, v11, v12, vcc
	v_sqrt_f32_e32 v12, v11
	s_nop 0
	v_add_u32_e32 v13, -1, v12
	v_fma_f32 v14, -v13, v12, v11
	v_cmp_ge_f32_e64 s[4:5], 0, v14
	v_add_u32_e32 v14, 1, v12
	s_nop 0
	v_cndmask_b32_e64 v13, v12, v13, s[4:5]
	v_fma_f32 v12, -v14, v12, v11
	v_cmp_lt_f32_e64 s[4:5], 0, v12
	s_nop 1
	v_cndmask_b32_e64 v12, v13, v14, s[4:5]
	v_mul_f32_e32 v13, 0x37800000, v12
	v_cndmask_b32_e32 v12, v12, v13, vcc
	v_cmp_class_f32_e32 vcc, v11, v245
	s_nop 1
	v_cndmask_b32_e32 v11, v12, v11, vcc
	v_div_scale_f32 v12, s[4:5], v11, v11, 1.0
	v_rcp_f32_e32 v13, v12
	s_or_b32 s4, s22, 5
	s_ashr_i32 s5, s4, 31
	s_lshl_b64 s[26:27], s[4:5], 11
	v_fma_f32 v14, -v12, v13, 1.0
	v_fmac_f32_e32 v13, v14, v13
	v_div_scale_f32 v14, vcc, 1.0, v11, 1.0
	v_mul_f32_e32 v15, v14, v13
	v_fma_f32 v17, -v12, v15, v14
	v_fmac_f32_e32 v15, v17, v13
	v_fma_f32 v12, -v12, v15, v14
	s_add_u32 s4, s6, s26
	v_div_fmas_f32 v12, v12, v13, v15
	s_addc_u32 s5, s7, s27
	v_div_fixup_f32 v11, v12, v11, 1.0
	s_waitcnt vmcnt(20)
	v_mov_b32_e32 v12, v104
	v_mov_b32_e32 v13, v105
	v_mov_b32_e32 v14, v106
	v_mov_b32_e32 v15, v107
	v_mov_b32_e32 v18, v108
	v_mov_b32_e32 v19, v109
	v_mov_b32_e32 v20, v110
	v_mov_b32_e32 v21, v111
	v_lshlrev_b32_e32 v17, 16, v12
	v_and_b32_e32 v22, 0xffff0000, v12
	v_add_f32_e32 v12, 0, v17
	v_lshlrev_b32_e32 v24, 16, v13
	v_add_f32_e32 v12, v12, v22
	v_and_b32_e32 v13, 0xffff0000, v13
	v_add_f32_e32 v12, v12, v24
	v_lshlrev_b32_e32 v26, 16, v14
	v_add_f32_e32 v12, v12, v13
	v_and_b32_e32 v14, 0xffff0000, v14
	v_add_f32_e32 v12, v12, v26
	v_lshlrev_b32_e32 v28, 16, v15
	v_add_f32_e32 v12, v12, v14
	v_and_b32_e32 v15, 0xffff0000, v15
	v_add_f32_e32 v12, v12, v28
	v_lshlrev_b32_e32 v23, 16, v18
	v_add_f32_e32 v12, v12, v15
	v_and_b32_e32 v18, 0xffff0000, v18
	v_add_f32_e32 v12, v12, v23
	v_lshlrev_b32_e32 v25, 16, v19
	v_add_f32_e32 v12, v12, v18
	v_and_b32_e32 v19, 0xffff0000, v19
	v_add_f32_e32 v12, v12, v25
	v_lshlrev_b32_e32 v27, 16, v20
	v_add_f32_e32 v12, v12, v19
	v_and_b32_e32 v20, 0xffff0000, v20
	v_add_f32_e32 v12, v12, v27
	v_lshlrev_b32_e32 v29, 16, v21
	v_add_f32_e32 v12, v12, v20
	v_and_b32_e32 v21, 0xffff0000, v21
	v_add_f32_e32 v12, v12, v29
	v_add_f32_e32 v12, v12, v21
	s_nop 1
	v_add_f32_dpp v12, v12, v12 quad_perm:[1,0,3,2] row_mask:0xf bank_mask:0xf bound_ctrl:1
	s_nop 1
	v_add_f32_dpp v12, v12, v12 quad_perm:[2,3,0,1] row_mask:0xf bank_mask:0xf bound_ctrl:1
	s_nop 1
	v_add_f32_dpp v12, v12, v12 row_half_mirror row_mask:0xf bank_mask:0xf bound_ctrl:1
	s_nop 1
	v_add_f32_dpp v12, v12, v12 row_mirror row_mask:0xf bank_mask:0xf bound_ctrl:1
	ds_swizzle_b32 v30, v12 offset:swizzle(SWAP,16)
	s_waitcnt lgkmcnt(0)
	v_add_f32_e32 v12, v12, v30
	v_mov_b32_e32 v30, v12
	s_nop 1
	v_permlane32_swap_b32_e32 v12, v30
	v_add_f32_e32 v12, v12, v30
	v_fmac_f32_e32 v22, 0xba800000, v12
	v_fmac_f32_e32 v17, 0xba800000, v12
	v_mul_f32_e32 v22, v22, v22
	v_fmac_f32_e32 v22, v17, v17
	v_fmac_f32_e32 v24, 0xba800000, v12
	v_fmac_f32_e32 v22, v24, v24
	v_fmac_f32_e32 v13, 0xba800000, v12
	v_fmac_f32_e32 v22, v13, v13
	v_fmac_f32_e32 v26, 0xba800000, v12
	v_fmac_f32_e32 v22, v26, v26
	v_fmac_f32_e32 v14, 0xba800000, v12
	v_fmac_f32_e32 v22, v14, v14
	v_fmac_f32_e32 v28, 0xba800000, v12
	v_fmac_f32_e32 v22, v28, v28
	v_fmac_f32_e32 v15, 0xba800000, v12
	v_fmac_f32_e32 v22, v15, v15
	v_fmac_f32_e32 v23, 0xba800000, v12
	v_fmac_f32_e32 v22, v23, v23
	v_fmac_f32_e32 v18, 0xba800000, v12
	v_fmac_f32_e32 v22, v18, v18
	v_fmac_f32_e32 v25, 0xba800000, v12
	v_fmac_f32_e32 v22, v25, v25
	v_fmac_f32_e32 v19, 0xba800000, v12
	v_fmac_f32_e32 v22, v19, v19
	v_fmac_f32_e32 v27, 0xba800000, v12
	v_fmac_f32_e32 v22, v27, v27
	v_fmac_f32_e32 v20, 0xba800000, v12
	v_fmac_f32_e32 v22, v20, v20
	v_fmac_f32_e32 v29, 0xba800000, v12
	v_fmac_f32_e32 v22, v29, v29
	v_fmac_f32_e32 v21, 0xba800000, v12
	v_fmac_f32_e32 v22, v21, v21
	s_nop 1
	v_add_f32_dpp v13, v22, v22 quad_perm:[1,0,3,2] row_mask:0xf bank_mask:0xf bound_ctrl:1
	s_nop 1
	v_add_f32_dpp v13, v13, v13 quad_perm:[2,3,0,1] row_mask:0xf bank_mask:0xf bound_ctrl:1
	s_nop 1
	v_add_f32_dpp v13, v13, v13 row_half_mirror row_mask:0xf bank_mask:0xf bound_ctrl:1
	s_nop 1
	v_add_f32_dpp v13, v13, v13 row_mirror row_mask:0xf bank_mask:0xf bound_ctrl:1
	ds_swizzle_b32 v14, v13 offset:swizzle(SWAP,16)
	s_waitcnt lgkmcnt(0)
	v_add_f32_e32 v13, v13, v14
	v_mov_b32_e32 v14, v13
	s_nop 1
	v_permlane32_swap_b32_e32 v13, v14
	v_add_f32_e32 v13, v13, v14
	v_fmamk_f32 v13, v13, 0x3a800000, v244
	v_cmp_gt_f32_e32 vcc, s81, v13
	v_mul_f32_e32 v14, 0x4f800000, v13
	s_nop 0
	v_cndmask_b32_e32 v13, v13, v14, vcc
	v_sqrt_f32_e32 v14, v13
	s_nop 0
	v_add_u32_e32 v15, -1, v14
	v_fma_f32 v17, -v15, v14, v13
	v_cmp_ge_f32_e64 s[4:5], 0, v17
	v_add_u32_e32 v17, 1, v14
	s_nop 0
	v_cndmask_b32_e64 v15, v14, v15, s[4:5]
	v_fma_f32 v14, -v17, v14, v13
	v_cmp_lt_f32_e64 s[4:5], 0, v14
	s_nop 1
	v_cndmask_b32_e64 v14, v15, v17, s[4:5]
	v_mul_f32_e32 v15, 0x37800000, v14
	v_cndmask_b32_e32 v14, v14, v15, vcc
	v_cmp_class_f32_e32 vcc, v13, v245
	s_nop 1
	v_cndmask_b32_e32 v13, v14, v13, vcc
	v_div_scale_f32 v14, s[4:5], v13, v13, 1.0
	v_rcp_f32_e32 v15, v14
	s_or_b32 s4, s22, 6
	s_ashr_i32 s5, s4, 31
	s_lshl_b64 s[36:37], s[4:5], 11
	v_fma_f32 v17, -v14, v15, 1.0
	v_fmac_f32_e32 v15, v17, v15
	v_div_scale_f32 v17, vcc, 1.0, v13, 1.0
	v_mul_f32_e32 v18, v17, v15
	v_fma_f32 v19, -v14, v18, v17
	v_fmac_f32_e32 v18, v19, v15
	s_add_u32 s4, s6, s36
	v_fma_f32 v14, -v14, v18, v17
	s_addc_u32 s5, s7, s37
	v_div_fmas_f32 v14, v14, v15, v18
	s_waitcnt vmcnt(18)
; __device__ __forceinline__ float bf_lo(unsigned v) { return __uint_as_float(v << 16); }
; __device__ __forceinline__ float bf_hi(unsigned v) { return __uint_as_float(v & 0xffff0000u); }
; __device__ __forceinline__ void sgu_item(int it, const bf16_t* GV, const bf16_t* ZU, const float* sg_, const float* sb_, const float* wsp, const float* bsp, bf16_t* CAT, unsigned char* lds, const int wv) {
;     ...
;         for (int i = 0; i < 16; ++i) { const bf16_t* row = GV + (size_t)(tok0 + 16 * wid + i) * 1024;
;             const u32x4 a = *(const u32x4*)(row + 8 * lane), c = *(const u32x4*)(row + 512 + 8 * lane);
;             float v[16];
; #pragma unroll
;             for (int k = 0; k < 4; ++k) { v[2 * k] = bf_lo(a[k]); v[2 * k + 1] = bf_hi(a[k]); v[8 + 2 * k] = bf_lo(c[k]); v[8 + 2 * k + 1] = bf_hi(c[k]); }
;             float s = 0.f;
; #pragma unroll
;             for (int k = 0; k < 16; ++k) s += v[k];
;             const float mu = wave_sum(s) * (1.0f / 1024.0f); float q = 0.f;
; #pragma unroll
;             for (int k = 0; k < 16; ++k) { const float d = v[k] - mu; q += d * d; }
;             mean[i] = mu; rstd[i] = 1.0f / sqrtf(wave_sum(q) * (1.0f / 1024.0f) + EPS); }
	v_mov_b32_e32 v18, v112
	v_mov_b32_e32 v19, v113
	v_mov_b32_e32 v20, v114
	v_mov_b32_e32 v21, v115
	v_mov_b32_e32 v22, v116
	v_mov_b32_e32 v23, v117
	v_mov_b32_e32 v24, v118
	v_mov_b32_e32 v25, v119
	v_div_fixup_f32 v13, v14, v13, 1.0
	v_lshlrev_b32_e32 v15, 16, v18
	v_and_b32_e32 v17, 0xffff0000, v18
	v_add_f32_e32 v14, 0, v15
	v_lshlrev_b32_e32 v26, 16, v19
	v_add_f32_e32 v14, v14, v17
	v_and_b32_e32 v19, 0xffff0000, v19
	v_add_f32_e32 v14, v14, v26
	v_lshlrev_b32_e32 v28, 16, v20
	v_add_f32_e32 v14, v14, v19
	v_and_b32_e32 v20, 0xffff0000, v20
	v_add_f32_e32 v14, v14, v28
	v_lshlrev_b32_e32 v30, 16, v21
	v_add_f32_e32 v14, v14, v20
	v_and_b32_e32 v21, 0xffff0000, v21
	v_add_f32_e32 v14, v14, v30
	v_lshlrev_b32_e32 v18, 16, v22
	v_add_f32_e32 v14, v14, v21
	v_and_b32_e32 v22, 0xffff0000, v22
	v_add_f32_e32 v14, v14, v18
	v_lshlrev_b32_e32 v27, 16, v23
	v_add_f32_e32 v14, v14, v22
	v_and_b32_e32 v23, 0xffff0000, v23
	v_add_f32_e32 v14, v14, v27
	v_lshlrev_b32_e32 v29, 16, v24
	v_add_f32_e32 v14, v14, v23
	v_and_b32_e32 v24, 0xffff0000, v24
	v_add_f32_e32 v14, v14, v29
	v_lshlrev_b32_e32 v31, 16, v25
	v_add_f32_e32 v14, v14, v24
	v_and_b32_e32 v25, 0xffff0000, v25
	v_add_f32_e32 v14, v14, v31
	v_add_f32_e32 v14, v14, v25
	s_nop 1
	v_add_f32_dpp v14, v14, v14 quad_perm:[1,0,3,2] row_mask:0xf bank_mask:0xf bound_ctrl:1
	s_nop 1
	v_add_f32_dpp v14, v14, v14 quad_perm:[2,3,0,1] row_mask:0xf bank_mask:0xf bound_ctrl:1
	s_nop 1
	v_add_f32_dpp v14, v14, v14 row_half_mirror row_mask:0xf bank_mask:0xf bound_ctrl:1
	s_nop 1
	v_add_f32_dpp v14, v14, v14 row_mirror row_mask:0xf bank_mask:0xf bound_ctrl:1
	ds_swizzle_b32 v32, v14 offset:swizzle(SWAP,16)
	s_waitcnt lgkmcnt(0)
	v_add_f32_e32 v14, v14, v32
	v_mov_b32_e32 v32, v14
	s_nop 1
	v_permlane32_swap_b32_e32 v14, v32
	v_add_f32_e32 v14, v14, v32
	v_fmac_f32_e32 v17, 0xba800000, v14
	v_fmac_f32_e32 v15, 0xba800000, v14
	v_mul_f32_e32 v17, v17, v17
	v_fmac_f32_e32 v17, v15, v15
	v_fmac_f32_e32 v26, 0xba800000, v14
	v_fmac_f32_e32 v17, v26, v26
	v_fmac_f32_e32 v19, 0xba800000, v14
	v_fmac_f32_e32 v17, v19, v19
	v_fmac_f32_e32 v28, 0xba800000, v14
	v_fmac_f32_e32 v17, v28, v28
	v_fmac_f32_e32 v20, 0xba800000, v14
	v_fmac_f32_e32 v17, v20, v20
	v_fmac_f32_e32 v30, 0xba800000, v14
	v_fmac_f32_e32 v17, v30, v30
	v_fmac_f32_e32 v21, 0xba800000, v14
	v_fmac_f32_e32 v17, v21, v21
	v_fmac_f32_e32 v18, 0xba800000, v14
	v_fmac_f32_e32 v17, v18, v18
	v_fmac_f32_e32 v22, 0xba800000, v14
	v_fmac_f32_e32 v17, v22, v22
	v_fmac_f32_e32 v27, 0xba800000, v14
	v_fmac_f32_e32 v17, v27, v27
	v_fmac_f32_e32 v23, 0xba800000, v14
	v_fmac_f32_e32 v17, v23, v23
	v_fmac_f32_e32 v29, 0xba800000, v14
	v_fmac_f32_e32 v17, v29, v29
	v_fmac_f32_e32 v24, 0xba800000, v14
	v_fmac_f32_e32 v17, v24, v24
	v_fmac_f32_e32 v31, 0xba800000, v14
	v_fmac_f32_e32 v17, v31, v31
	v_fmac_f32_e32 v25, 0xba800000, v14
	v_fmac_f32_e32 v17, v25, v25
	s_nop 1
	v_add_f32_dpp v15, v17, v17 quad_perm:[1,0,3,2] row_mask:0xf bank_mask:0xf bound_ctrl:1
	s_nop 1
	v_add_f32_dpp v15, v15, v15 quad_perm:[2,3,0,1] row_mask:0xf bank_mask:0xf bound_ctrl:1
	s_nop 1
	v_add_f32_dpp v15, v15, v15 row_half_mirror row_mask:0xf bank_mask:0xf bound_ctrl:1
	s_nop 1
	v_add_f32_dpp v15, v15, v15 row_mirror row_mask:0xf bank_mask:0xf bound_ctrl:1
	ds_swizzle_b32 v17, v15 offset:swizzle(SWAP,16)
	s_waitcnt lgkmcnt(0)
	v_add_f32_e32 v15, v15, v17
	v_mov_b32_e32 v17, v15
	s_nop 1
	v_permlane32_swap_b32_e32 v15, v17
	v_add_f32_e32 v15, v15, v17
	v_fmamk_f32 v15, v15, 0x3a800000, v244
	v_cmp_gt_f32_e32 vcc, s81, v15
	v_mul_f32_e32 v17, 0x4f800000, v15
	s_nop 0
	v_cndmask_b32_e32 v15, v15, v17, vcc
	v_sqrt_f32_e32 v17, v15
	s_nop 0
	v_add_u32_e32 v18, -1, v17
	v_fma_f32 v19, -v18, v17, v15
	v_cmp_ge_f32_e64 s[4:5], 0, v19
	v_add_u32_e32 v19, 1, v17
	s_nop 0
	v_cndmask_b32_e64 v18, v17, v18, s[4:5]
	v_fma_f32 v17, -v19, v17, v15
	v_cmp_lt_f32_e64 s[4:5], 0, v17
	s_nop 1
	v_cndmask_b32_e64 v17, v18, v19, s[4:5]
	v_mul_f32_e32 v18, 0x37800000, v17
	v_cndmask_b32_e32 v17, v17, v18, vcc
	v_cmp_class_f32_e32 vcc, v15, v245
	s_nop 1
	v_cndmask_b32_e32 v15, v17, v15, vcc
	v_div_scale_f32 v17, s[4:5], v15, v15, 1.0
	v_rcp_f32_e32 v18, v17
	s_or_b32 s4, s22, 7
	s_ashr_i32 s5, s4, 31
	s_lshl_b64 s[42:43], s[4:5], 11
	v_fma_f32 v19, -v17, v18, 1.0
	v_fmac_f32_e32 v18, v19, v18
	v_div_scale_f32 v19, vcc, 1.0, v15, 1.0
	v_mul_f32_e32 v20, v19, v18
	v_fma_f32 v21, -v17, v20, v19
	v_fmac_f32_e32 v20, v21, v18
	s_add_u32 s4, s6, s42
	v_fma_f32 v17, -v17, v20, v19
	s_addc_u32 s5, s7, s43
	v_div_fmas_f32 v17, v17, v18, v20
	s_waitcnt vmcnt(16)
	v_mov_b32_e32 v18, v120
	v_mov_b32_e32 v19, v121
	v_mov_b32_e32 v20, v122
	v_mov_b32_e32 v21, v123
	v_mov_b32_e32 v22, v124
	v_mov_b32_e32 v23, v125
	v_mov_b32_e32 v24, v126
	v_mov_b32_e32 v25, v127
	v_div_fixup_f32 v15, v17, v15, 1.0
	v_lshlrev_b32_e32 v26, 16, v18
	v_and_b32_e32 v18, 0xffff0000, v18
	v_add_f32_e32 v17, 0, v26
	v_lshlrev_b32_e32 v28, 16, v19
	v_add_f32_e32 v17, v17, v18
	v_and_b32_e32 v19, 0xffff0000, v19
	v_add_f32_e32 v17, v17, v28
	v_lshlrev_b32_e32 v30, 16, v20
	v_add_f32_e32 v17, v17, v19
	v_and_b32_e32 v20, 0xffff0000, v20
	v_add_f32_e32 v17, v17, v30
	v_lshlrev_b32_e32 v32, 16, v21
	v_add_f32_e32 v17, v17, v20
	v_and_b32_e32 v21, 0xffff0000, v21
	v_add_f32_e32 v17, v17, v32
	v_lshlrev_b32_e32 v27, 16, v22
	v_add_f32_e32 v17, v17, v21
	v_and_b32_e32 v22, 0xffff0000, v22
	v_add_f32_e32 v17, v17, v27
	v_lshlrev_b32_e32 v29, 16, v23
	v_add_f32_e32 v17, v17, v22
	v_and_b32_e32 v23, 0xffff0000, v23
	v_add_f32_e32 v17, v17, v29
	v_lshlrev_b32_e32 v31, 16, v24
	v_add_f32_e32 v17, v17, v23
	v_and_b32_e32 v24, 0xffff0000, v24
	v_add_f32_e32 v17, v17, v31
	v_lshlrev_b32_e32 v33, 16, v25
	v_add_f32_e32 v17, v17, v24
	v_and_b32_e32 v25, 0xffff0000, v25
	v_add_f32_e32 v17, v17, v33
	v_add_f32_e32 v17, v17, v25
	s_nop 1
	v_add_f32_dpp v17, v17, v17 quad_perm:[1,0,3,2] row_mask:0xf bank_mask:0xf bound_ctrl:1
	s_nop 1
	v_add_f32_dpp v17, v17, v17 quad_perm:[2,3,0,1] row_mask:0xf bank_mask:0xf bound_ctrl:1
	s_nop 1
	v_add_f32_dpp v17, v17, v17 row_half_mirror row_mask:0xf bank_mask:0xf bound_ctrl:1
	s_nop 1
	v_add_f32_dpp v17, v17, v17 row_mirror row_mask:0xf bank_mask:0xf bound_ctrl:1
	ds_swizzle_b32 v34, v17 offset:swizzle(SWAP,16)
	s_waitcnt lgkmcnt(0)
; __device__ __forceinline__ float bf_lo(unsigned v) { return __uint_as_float(v << 16); }
; __device__ __forceinline__ float bf_hi(unsigned v) { return __uint_as_float(v & 0xffff0000u); }
; __device__ __forceinline__ void sgu_item(int it, const bf16_t* GV, const bf16_t* ZU, const float* sg_, const float* sb_, const float* wsp, const float* bsp, bf16_t* CAT, unsigned char* lds, const int wv) {
;     ...
;         for (int i = 0; i < 16; ++i) { const bf16_t* row = GV + (size_t)(tok0 + 16 * wid + i) * 1024;
;             const u32x4 a = *(const u32x4*)(row + 8 * lane), c = *(const u32x4*)(row + 512 + 8 * lane);
;             float v[16];
; #pragma unroll
;             for (int k = 0; k < 4; ++k) { v[2 * k] = bf_lo(a[k]); v[2 * k + 1] = bf_hi(a[k]); v[8 + 2 * k] = bf_lo(c[k]); v[8 + 2 * k + 1] = bf_hi(c[k]); }
;             float s = 0.f;
; #pragma unroll
;             for (int k = 0; k < 16; ++k) s += v[k];
;             const float mu = wave_sum(s) * (1.0f / 1024.0f); float q = 0.f;
; #pragma unroll
;             for (int k = 0; k < 16; ++k) { const float d = v[k] - mu; q += d * d; }
;             mean[i] = mu; rstd[i] = 1.0f / sqrtf(wave_sum(q) * (1.0f / 1024.0f) + EPS); }
	v_add_f32_e32 v17, v17, v34
	v_mov_b32_e32 v34, v17
	s_nop 1
	v_permlane32_swap_b32_e32 v17, v34
	v_add_f32_e32 v17, v17, v34
	v_fmac_f32_e32 v18, 0xba800000, v17
	v_fmac_f32_e32 v26, 0xba800000, v17
	v_mul_f32_e32 v18, v18, v18
	v_fmac_f32_e32 v18, v26, v26
	v_fmac_f32_e32 v28, 0xba800000, v17
	v_fmac_f32_e32 v18, v28, v28
	v_fmac_f32_e32 v19, 0xba800000, v17
	v_fmac_f32_e32 v18, v19, v19
	v_fmac_f32_e32 v30, 0xba800000, v17
	v_fmac_f32_e32 v18, v30, v30
	v_fmac_f32_e32 v20, 0xba800000, v17
	v_fmac_f32_e32 v18, v20, v20
	v_fmac_f32_e32 v32, 0xba800000, v17
	v_fmac_f32_e32 v18, v32, v32
	v_fmac_f32_e32 v21, 0xba800000, v17
	v_fmac_f32_e32 v18, v21, v21
	v_fmac_f32_e32 v27, 0xba800000, v17
	v_fmac_f32_e32 v18, v27, v27
	v_fmac_f32_e32 v22, 0xba800000, v17
	v_fmac_f32_e32 v18, v22, v22
	v_fmac_f32_e32 v29, 0xba800000, v17
	v_fmac_f32_e32 v18, v29, v29
	v_fmac_f32_e32 v23, 0xba800000, v17
	v_fmac_f32_e32 v18, v23, v23
	v_fmac_f32_e32 v31, 0xba800000, v17
	v_fmac_f32_e32 v18, v31, v31
	v_fmac_f32_e32 v24, 0xba800000, v17
	v_fmac_f32_e32 v18, v24, v24
	v_fmac_f32_e32 v33, 0xba800000, v17
	v_fmac_f32_e32 v18, v33, v33
	v_fmac_f32_e32 v25, 0xba800000, v17
	v_fmac_f32_e32 v18, v25, v25
	s_nop 1
	v_add_f32_dpp v18, v18, v18 quad_perm:[1,0,3,2] row_mask:0xf bank_mask:0xf bound_ctrl:1
	s_nop 1
	v_add_f32_dpp v18, v18, v18 quad_perm:[2,3,0,1] row_mask:0xf bank_mask:0xf bound_ctrl:1
	s_nop 1
	v_add_f32_dpp v18, v18, v18 row_half_mirror row_mask:0xf bank_mask:0xf bound_ctrl:1
	s_nop 1
	v_add_f32_dpp v18, v18, v18 row_mirror row_mask:0xf bank_mask:0xf bound_ctrl:1
	ds_swizzle_b32 v19, v18 offset:swizzle(SWAP,16)
	s_waitcnt lgkmcnt(0)
	v_add_f32_e32 v18, v18, v19
	v_mov_b32_e32 v19, v18
	s_nop 1
	v_permlane32_swap_b32_e32 v18, v19
	v_add_f32_e32 v18, v18, v19
	v_fmamk_f32 v18, v18, 0x3a800000, v244
	v_cmp_gt_f32_e32 vcc, s81, v18
	v_mul_f32_e32 v19, 0x4f800000, v18
	s_nop 0
	v_cndmask_b32_e32 v18, v18, v19, vcc
	v_sqrt_f32_e32 v19, v18
	s_nop 0
	v_add_u32_e32 v20, -1, v19
	v_fma_f32 v21, -v20, v19, v18
	v_cmp_ge_f32_e64 s[4:5], 0, v21
	v_add_u32_e32 v21, 1, v19
	s_nop 0
	v_cndmask_b32_e64 v20, v19, v20, s[4:5]
	v_fma_f32 v19, -v21, v19, v18
	v_cmp_lt_f32_e64 s[4:5], 0, v19
	s_nop 1
	v_cndmask_b32_e64 v19, v20, v21, s[4:5]
	v_mul_f32_e32 v20, 0x37800000, v19
	v_cndmask_b32_e32 v19, v19, v20, vcc
	v_cmp_class_f32_e32 vcc, v18, v245
	s_nop 1
	v_cndmask_b32_e32 v18, v19, v18, vcc
	v_div_scale_f32 v19, s[4:5], v18, v18, 1.0
	v_rcp_f32_e32 v20, v19
	s_or_b32 s4, s22, 8
	s_ashr_i32 s5, s4, 31
	s_lshl_b64 s[44:45], s[4:5], 11
	v_fma_f32 v21, -v19, v20, 1.0
	v_fmac_f32_e32 v20, v21, v20
	v_div_scale_f32 v21, vcc, 1.0, v18, 1.0
	v_mul_f32_e32 v22, v21, v20
	v_fma_f32 v23, -v19, v22, v21
	v_fmac_f32_e32 v22, v23, v20
	s_add_u32 s4, s6, s44
	v_fma_f32 v19, -v19, v22, v21
	s_addc_u32 s5, s7, s45
	v_div_fmas_f32 v19, v19, v20, v22
	s_waitcnt vmcnt(14)
	v_mov_b32_e32 v20, v128
	v_mov_b32_e32 v21, v129
	v_mov_b32_e32 v22, v130
	v_mov_b32_e32 v23, v131
	v_mov_b32_e32 v24, v132
	v_mov_b32_e32 v25, v133
	v_mov_b32_e32 v26, v134
	v_mov_b32_e32 v27, v135
	v_div_fixup_f32 v18, v19, v18, 1.0
	v_lshlrev_b32_e32 v28, 16, v20
	v_and_b32_e32 v20, 0xffff0000, v20
	v_add_f32_e32 v19, 0, v28
	v_lshlrev_b32_e32 v30, 16, v21
	v_add_f32_e32 v19, v19, v20
	v_and_b32_e32 v21, 0xffff0000, v21
	v_add_f32_e32 v19, v19, v30
	v_lshlrev_b32_e32 v32, 16, v22
	v_add_f32_e32 v19, v19, v21
	v_and_b32_e32 v22, 0xffff0000, v22
	v_add_f32_e32 v19, v19, v32
	v_lshlrev_b32_e32 v34, 16, v23
	v_add_f32_e32 v19, v19, v22
	v_and_b32_e32 v23, 0xffff0000, v23
	v_add_f32_e32 v19, v19, v34
	v_lshlrev_b32_e32 v29, 16, v24
	v_add_f32_e32 v19, v19, v23
	v_and_b32_e32 v24, 0xffff0000, v24
	v_add_f32_e32 v19, v19, v29
	v_lshlrev_b32_e32 v31, 16, v25
	v_add_f32_e32 v19, v19, v24
	v_and_b32_e32 v25, 0xffff0000, v25
	v_add_f32_e32 v19, v19, v31
	v_lshlrev_b32_e32 v33, 16, v26
	v_add_f32_e32 v19, v19, v25
	v_and_b32_e32 v26, 0xffff0000, v26
	v_add_f32_e32 v19, v19, v33
	v_lshlrev_b32_e32 v35, 16, v27
	v_add_f32_e32 v19, v19, v26
	v_and_b32_e32 v27, 0xffff0000, v27
	v_add_f32_e32 v19, v19, v35
	v_add_f32_e32 v19, v19, v27
	s_nop 1
	v_add_f32_dpp v19, v19, v19 quad_perm:[1,0,3,2] row_mask:0xf bank_mask:0xf bound_ctrl:1
	s_nop 1
	v_add_f32_dpp v19, v19, v19 quad_perm:[2,3,0,1] row_mask:0xf bank_mask:0xf bound_ctrl:1
	s_nop 1
	v_add_f32_dpp v19, v19, v19 row_half_mirror row_mask:0xf bank_mask:0xf bound_ctrl:1
	s_nop 1
	v_add_f32_dpp v19, v19, v19 row_mirror row_mask:0xf bank_mask:0xf bound_ctrl:1
	ds_swizzle_b32 v36, v19 offset:swizzle(SWAP,16)
	s_waitcnt lgkmcnt(0)
	v_add_f32_e32 v19, v19, v36
	v_mov_b32_e32 v36, v19
	s_nop 1
	v_permlane32_swap_b32_e32 v19, v36
	v_add_f32_e32 v19, v19, v36
	v_fmac_f32_e32 v20, 0xba800000, v19
	v_fmac_f32_e32 v28, 0xba800000, v19
	v_mul_f32_e32 v20, v20, v20
	v_fmac_f32_e32 v20, v28, v28
	v_fmac_f32_e32 v30, 0xba800000, v19
	v_fmac_f32_e32 v20, v30, v30
	v_fmac_f32_e32 v21, 0xba800000, v19
	v_fmac_f32_e32 v20, v21, v21
	v_fmac_f32_e32 v32, 0xba800000, v19
	v_fmac_f32_e32 v20, v32, v32
	v_fmac_f32_e32 v22, 0xba800000, v19
	v_fmac_f32_e32 v20, v22, v22
	v_fmac_f32_e32 v34, 0xba800000, v19
	v_fmac_f32_e32 v20, v34, v34
	v_fmac_f32_e32 v23, 0xba800000, v19
	v_fmac_f32_e32 v20, v23, v23
	v_fmac_f32_e32 v29, 0xba800000, v19
	v_fmac_f32_e32 v20, v29, v29
	v_fmac_f32_e32 v24, 0xba800000, v19
	v_fmac_f32_e32 v20, v24, v24
	v_fmac_f32_e32 v31, 0xba800000, v19
	v_fmac_f32_e32 v20, v31, v31
	v_fmac_f32_e32 v25, 0xba800000, v19
	v_fmac_f32_e32 v20, v25, v25
	v_fmac_f32_e32 v33, 0xba800000, v19
	v_fmac_f32_e32 v20, v33, v33
	v_fmac_f32_e32 v26, 0xba800000, v19
	v_fmac_f32_e32 v20, v26, v26
	v_fmac_f32_e32 v35, 0xba800000, v19
	v_fmac_f32_e32 v20, v35, v35
	v_fmac_f32_e32 v27, 0xba800000, v19
	v_fmac_f32_e32 v20, v27, v27
	s_nop 1
	v_add_f32_dpp v20, v20, v20 quad_perm:[1,0,3,2] row_mask:0xf bank_mask:0xf bound_ctrl:1
	s_nop 1
	v_add_f32_dpp v20, v20, v20 quad_perm:[2,3,0,1] row_mask:0xf bank_mask:0xf bound_ctrl:1
	s_nop 1
	v_add_f32_dpp v20, v20, v20 row_half_mirror row_mask:0xf bank_mask:0xf bound_ctrl:1
	s_nop 1
	v_add_f32_dpp v20, v20, v20 row_mirror row_mask:0xf bank_mask:0xf bound_ctrl:1
	ds_swizzle_b32 v21, v20 offset:swizzle(SWAP,16)
	s_waitcnt lgkmcnt(0)
; __device__ __forceinline__ float bf_lo(unsigned v) { return __uint_as_float(v << 16); }
; __device__ __forceinline__ float bf_hi(unsigned v) { return __uint_as_float(v & 0xffff0000u); }
; __device__ __forceinline__ void sgu_item(int it, const bf16_t* GV, const bf16_t* ZU, const float* sg_, const float* sb_, const float* wsp, const float* bsp, bf16_t* CAT, unsigned char* lds, const int wv) {
;     ...
;         for (int i = 0; i < 16; ++i) { const bf16_t* row = GV + (size_t)(tok0 + 16 * wid + i) * 1024;
;             const u32x4 a = *(const u32x4*)(row + 8 * lane), c = *(const u32x4*)(row + 512 + 8 * lane);
;             float v[16];
; #pragma unroll
;             for (int k = 0; k < 4; ++k) { v[2 * k] = bf_lo(a[k]); v[2 * k + 1] = bf_hi(a[k]); v[8 + 2 * k] = bf_lo(c[k]); v[8 + 2 * k + 1] = bf_hi(c[k]); }
;             float s = 0.f;
; #pragma unroll
;             for (int k = 0; k < 16; ++k) s += v[k];
;             const float mu = wave_sum(s) * (1.0f / 1024.0f); float q = 0.f;
; #pragma unroll
;             for (int k = 0; k < 16; ++k) { const float d = v[k] - mu; q += d * d; }
;             mean[i] = mu; rstd[i] = 1.0f / sqrtf(wave_sum(q) * (1.0f / 1024.0f) + EPS); }
	v_add_f32_e32 v20, v20, v21
	v_mov_b32_e32 v21, v20
	s_nop 1
	v_permlane32_swap_b32_e32 v20, v21
	v_add_f32_e32 v20, v20, v21
	v_fmamk_f32 v20, v20, 0x3a800000, v244
	v_cmp_gt_f32_e32 vcc, s81, v20
	v_mul_f32_e32 v21, 0x4f800000, v20
	s_nop 0
	v_cndmask_b32_e32 v20, v20, v21, vcc
	v_sqrt_f32_e32 v21, v20
	s_nop 0
	v_add_u32_e32 v22, -1, v21
	v_fma_f32 v23, -v22, v21, v20
	v_cmp_ge_f32_e64 s[4:5], 0, v23
	v_add_u32_e32 v23, 1, v21
	s_nop 0
	v_cndmask_b32_e64 v22, v21, v22, s[4:5]
	v_fma_f32 v21, -v23, v21, v20
	v_cmp_lt_f32_e64 s[4:5], 0, v21
	s_nop 1
	v_cndmask_b32_e64 v21, v22, v23, s[4:5]
	v_mul_f32_e32 v22, 0x37800000, v21
	v_cndmask_b32_e32 v21, v21, v22, vcc
	v_cmp_class_f32_e32 vcc, v20, v245
	s_nop 1
	v_cndmask_b32_e32 v20, v21, v20, vcc
	v_div_scale_f32 v21, s[4:5], v20, v20, 1.0
	v_rcp_f32_e32 v22, v21
	s_or_b32 s4, s22, 9
	s_ashr_i32 s5, s4, 31
	s_lshl_b64 s[10:11], s[4:5], 11
	v_fma_f32 v23, -v21, v22, 1.0
	v_fmac_f32_e32 v22, v23, v22
	v_div_scale_f32 v23, vcc, 1.0, v20, 1.0
	v_mul_f32_e32 v24, v23, v22
	v_fma_f32 v25, -v21, v24, v23
	v_fmac_f32_e32 v24, v25, v22
	s_add_u32 s4, s6, s10
	v_fma_f32 v21, -v21, v24, v23
	s_addc_u32 s5, s7, s11
	v_div_fmas_f32 v21, v21, v22, v24
	s_waitcnt vmcnt(12)
	v_mov_b32_e32 v22, v136
	v_mov_b32_e32 v23, v137
	v_mov_b32_e32 v24, v138
	v_mov_b32_e32 v25, v139
	v_mov_b32_e32 v26, v140
	v_mov_b32_e32 v27, v141
	v_mov_b32_e32 v28, v142
	v_mov_b32_e32 v29, v143
	v_div_fixup_f32 v20, v21, v20, 1.0
	v_lshlrev_b32_e32 v30, 16, v22
	v_and_b32_e32 v22, 0xffff0000, v22
	v_add_f32_e32 v21, 0, v30
	v_lshlrev_b32_e32 v32, 16, v23
	v_add_f32_e32 v21, v21, v22
	v_and_b32_e32 v23, 0xffff0000, v23
	v_add_f32_e32 v21, v21, v32
	v_lshlrev_b32_e32 v34, 16, v24
	v_add_f32_e32 v21, v21, v23
	v_and_b32_e32 v24, 0xffff0000, v24
	v_add_f32_e32 v21, v21, v34
	v_lshlrev_b32_e32 v36, 16, v25
	v_add_f32_e32 v21, v21, v24
	v_and_b32_e32 v25, 0xffff0000, v25
	v_add_f32_e32 v21, v21, v36
	v_lshlrev_b32_e32 v31, 16, v26
	v_add_f32_e32 v21, v21, v25
	v_and_b32_e32 v26, 0xffff0000, v26
	v_add_f32_e32 v21, v21, v31
	v_lshlrev_b32_e32 v33, 16, v27
	v_add_f32_e32 v21, v21, v26
	v_and_b32_e32 v27, 0xffff0000, v27
	v_add_f32_e32 v21, v21, v33
	v_lshlrev_b32_e32 v35, 16, v28
	v_add_f32_e32 v21, v21, v27
	v_and_b32_e32 v28, 0xffff0000, v28
	v_add_f32_e32 v21, v21, v35
	v_lshlrev_b32_e32 v37, 16, v29
	v_add_f32_e32 v21, v21, v28
	v_and_b32_e32 v29, 0xffff0000, v29
	v_add_f32_e32 v21, v21, v37
	v_add_f32_e32 v21, v21, v29
	s_nop 1
	v_add_f32_dpp v21, v21, v21 quad_perm:[1,0,3,2] row_mask:0xf bank_mask:0xf bound_ctrl:1
	s_nop 1
	v_add_f32_dpp v21, v21, v21 quad_perm:[2,3,0,1] row_mask:0xf bank_mask:0xf bound_ctrl:1
	s_nop 1
	v_add_f32_dpp v21, v21, v21 row_half_mirror row_mask:0xf bank_mask:0xf bound_ctrl:1
	s_nop 1
	v_add_f32_dpp v21, v21, v21 row_mirror row_mask:0xf bank_mask:0xf bound_ctrl:1
	ds_swizzle_b32 v38, v21 offset:swizzle(SWAP,16)
	s_waitcnt lgkmcnt(0)
	v_add_f32_e32 v21, v21, v38
	v_mov_b32_e32 v38, v21
	s_nop 1
	v_permlane32_swap_b32_e32 v21, v38
	v_add_f32_e32 v21, v21, v38
	v_fmac_f32_e32 v22, 0xba800000, v21
	v_fmac_f32_e32 v30, 0xba800000, v21
	v_mul_f32_e32 v22, v22, v22
	v_fmac_f32_e32 v22, v30, v30
	v_fmac_f32_e32 v32, 0xba800000, v21
	v_fmac_f32_e32 v22, v32, v32
	v_fmac_f32_e32 v23, 0xba800000, v21
	v_fmac_f32_e32 v22, v23, v23
	v_fmac_f32_e32 v34, 0xba800000, v21
	v_fmac_f32_e32 v22, v34, v34
	v_fmac_f32_e32 v24, 0xba800000, v21
	v_fmac_f32_e32 v22, v24, v24
	v_fmac_f32_e32 v36, 0xba800000, v21
	v_fmac_f32_e32 v22, v36, v36
	v_fmac_f32_e32 v25, 0xba800000, v21
	v_fmac_f32_e32 v22, v25, v25
	v_fmac_f32_e32 v31, 0xba800000, v21
	v_fmac_f32_e32 v22, v31, v31
	v_fmac_f32_e32 v26, 0xba800000, v21
	v_fmac_f32_e32 v22, v26, v26
	v_fmac_f32_e32 v33, 0xba800000, v21
	v_fmac_f32_e32 v22, v33, v33
	v_fmac_f32_e32 v27, 0xba800000, v21
	v_fmac_f32_e32 v22, v27, v27
	v_fmac_f32_e32 v35, 0xba800000, v21
	v_fmac_f32_e32 v22, v35, v35
	v_fmac_f32_e32 v28, 0xba800000, v21
	v_fmac_f32_e32 v22, v28, v28
	v_fmac_f32_e32 v37, 0xba800000, v21
	v_fmac_f32_e32 v22, v37, v37
	v_fmac_f32_e32 v29, 0xba800000, v21
	v_fmac_f32_e32 v22, v29, v29
	s_nop 1
	v_add_f32_dpp v22, v22, v22 quad_perm:[1,0,3,2] row_mask:0xf bank_mask:0xf bound_ctrl:1
	s_nop 1
	v_add_f32_dpp v22, v22, v22 quad_perm:[2,3,0,1] row_mask:0xf bank_mask:0xf bound_ctrl:1
	s_nop 1
	v_add_f32_dpp v22, v22, v22 row_half_mirror row_mask:0xf bank_mask:0xf bound_ctrl:1
	s_nop 1
	v_add_f32_dpp v22, v22, v22 row_mirror row_mask:0xf bank_mask:0xf bound_ctrl:1
	ds_swizzle_b32 v23, v22 offset:swizzle(SWAP,16)
	s_waitcnt lgkmcnt(0)
	v_add_f32_e32 v22, v22, v23
	v_mov_b32_e32 v23, v22
	s_nop 1
	v_permlane32_swap_b32_e32 v22, v23
	v_add_f32_e32 v22, v22, v23
	v_fmamk_f32 v22, v22, 0x3a800000, v244
	v_cmp_gt_f32_e32 vcc, s81, v22
	v_mul_f32_e32 v23, 0x4f800000, v22
	s_nop 0
	v_cndmask_b32_e32 v22, v22, v23, vcc
	v_sqrt_f32_e32 v23, v22
	s_nop 0
	v_add_u32_e32 v24, -1, v23
	v_fma_f32 v25, -v24, v23, v22
	v_cmp_ge_f32_e64 s[4:5], 0, v25
	v_add_u32_e32 v25, 1, v23
	s_nop 0
	v_cndmask_b32_e64 v24, v23, v24, s[4:5]
	v_fma_f32 v23, -v25, v23, v22
	v_cmp_lt_f32_e64 s[4:5], 0, v23
	s_nop 1
	v_cndmask_b32_e64 v23, v24, v25, s[4:5]
	v_mul_f32_e32 v24, 0x37800000, v23
	v_cndmask_b32_e32 v23, v23, v24, vcc
	v_cmp_class_f32_e32 vcc, v22, v245
	s_nop 1
	v_cndmask_b32_e32 v22, v23, v22, vcc
	v_div_scale_f32 v23, s[4:5], v22, v22, 1.0
	v_rcp_f32_e32 v24, v23
	s_or_b32 s4, s22, 10
	s_ashr_i32 s5, s4, 31
	s_lshl_b64 s[12:13], s[4:5], 11
	v_fma_f32 v25, -v23, v24, 1.0
	v_fmac_f32_e32 v24, v25, v24
	v_div_scale_f32 v25, vcc, 1.0, v22, 1.0
	v_mul_f32_e32 v26, v25, v24
	v_fma_f32 v27, -v23, v26, v25
	v_fmac_f32_e32 v26, v27, v24
	s_add_u32 s4, s6, s12
	v_fma_f32 v23, -v23, v26, v25
	s_addc_u32 s5, s7, s13
	v_div_fmas_f32 v23, v23, v24, v26
	s_waitcnt vmcnt(10)
; __device__ __forceinline__ float bf_lo(unsigned v) { return __uint_as_float(v << 16); }
; __device__ __forceinline__ float bf_hi(unsigned v) { return __uint_as_float(v & 0xffff0000u); }
; __device__ __forceinline__ void sgu_item(int it, const bf16_t* GV, const bf16_t* ZU, const float* sg_, const float* sb_, const float* wsp, const float* bsp, bf16_t* CAT, unsigned char* lds, const int wv) {
;     ...
;         for (int i = 0; i < 16; ++i) { const bf16_t* row = GV + (size_t)(tok0 + 16 * wid + i) * 1024;
;             const u32x4 a = *(const u32x4*)(row + 8 * lane), c = *(const u32x4*)(row + 512 + 8 * lane);
;             float v[16];
; #pragma unroll
;             for (int k = 0; k < 4; ++k) { v[2 * k] = bf_lo(a[k]); v[2 * k + 1] = bf_hi(a[k]); v[8 + 2 * k] = bf_lo(c[k]); v[8 + 2 * k + 1] = bf_hi(c[k]); }
;             float s = 0.f;
; #pragma unroll
;             for (int k = 0; k < 16; ++k) s += v[k];
;             const float mu = wave_sum(s) * (1.0f / 1024.0f); float q = 0.f;
; #pragma unroll
;             for (int k = 0; k < 16; ++k) { const float d = v[k] - mu; q += d * d; }
;             mean[i] = mu; rstd[i] = 1.0f / sqrtf(wave_sum(q) * (1.0f / 1024.0f) + EPS); }
	v_mov_b32_e32 v24, v144
	v_mov_b32_e32 v25, v145
	v_mov_b32_e32 v26, v146
	v_mov_b32_e32 v27, v147
	v_mov_b32_e32 v28, v148
	v_mov_b32_e32 v29, v149
	v_mov_b32_e32 v30, v150
	v_mov_b32_e32 v31, v151
	v_div_fixup_f32 v22, v23, v22, 1.0
	v_lshlrev_b32_e32 v32, 16, v24
	v_and_b32_e32 v24, 0xffff0000, v24
	v_add_f32_e32 v23, 0, v32
	v_lshlrev_b32_e32 v34, 16, v25
	v_add_f32_e32 v23, v23, v24
	v_and_b32_e32 v25, 0xffff0000, v25
	v_add_f32_e32 v23, v23, v34
	v_lshlrev_b32_e32 v36, 16, v26
	v_add_f32_e32 v23, v23, v25
	v_and_b32_e32 v26, 0xffff0000, v26
	v_add_f32_e32 v23, v23, v36
	v_lshlrev_b32_e32 v38, 16, v27
	v_add_f32_e32 v23, v23, v26
	v_and_b32_e32 v27, 0xffff0000, v27
	v_add_f32_e32 v23, v23, v38
	v_lshlrev_b32_e32 v33, 16, v28
	v_add_f32_e32 v23, v23, v27
	v_and_b32_e32 v28, 0xffff0000, v28
	v_add_f32_e32 v23, v23, v33
	v_lshlrev_b32_e32 v35, 16, v29
	v_add_f32_e32 v23, v23, v28
	v_and_b32_e32 v29, 0xffff0000, v29
	v_add_f32_e32 v23, v23, v35
	v_lshlrev_b32_e32 v37, 16, v30
	v_add_f32_e32 v23, v23, v29
	v_and_b32_e32 v30, 0xffff0000, v30
	v_add_f32_e32 v23, v23, v37
	v_lshlrev_b32_e32 v39, 16, v31
	v_add_f32_e32 v23, v23, v30
	v_and_b32_e32 v31, 0xffff0000, v31
	v_add_f32_e32 v23, v23, v39
	v_add_f32_e32 v23, v23, v31
	s_nop 1
	v_add_f32_dpp v23, v23, v23 quad_perm:[1,0,3,2] row_mask:0xf bank_mask:0xf bound_ctrl:1
	s_nop 1
	v_add_f32_dpp v23, v23, v23 quad_perm:[2,3,0,1] row_mask:0xf bank_mask:0xf bound_ctrl:1
	s_nop 1
	v_add_f32_dpp v23, v23, v23 row_half_mirror row_mask:0xf bank_mask:0xf bound_ctrl:1
	s_nop 1
	v_add_f32_dpp v23, v23, v23 row_mirror row_mask:0xf bank_mask:0xf bound_ctrl:1
	ds_swizzle_b32 v40, v23 offset:swizzle(SWAP,16)
	s_waitcnt lgkmcnt(0)
	v_add_f32_e32 v23, v23, v40
	v_mov_b32_e32 v40, v23
	s_nop 1
	v_permlane32_swap_b32_e32 v23, v40
	v_add_f32_e32 v23, v23, v40
	v_fmac_f32_e32 v24, 0xba800000, v23
	v_fmac_f32_e32 v32, 0xba800000, v23
	v_mul_f32_e32 v24, v24, v24
	v_fmac_f32_e32 v24, v32, v32
	v_fmac_f32_e32 v34, 0xba800000, v23
	v_fmac_f32_e32 v24, v34, v34
	v_fmac_f32_e32 v25, 0xba800000, v23
	v_fmac_f32_e32 v24, v25, v25
	v_fmac_f32_e32 v36, 0xba800000, v23
	v_fmac_f32_e32 v24, v36, v36
	v_fmac_f32_e32 v26, 0xba800000, v23
	v_fmac_f32_e32 v24, v26, v26
	v_fmac_f32_e32 v38, 0xba800000, v23
	v_fmac_f32_e32 v24, v38, v38
	v_fmac_f32_e32 v27, 0xba800000, v23
	v_fmac_f32_e32 v24, v27, v27
	v_fmac_f32_e32 v33, 0xba800000, v23
	v_fmac_f32_e32 v24, v33, v33
	v_fmac_f32_e32 v28, 0xba800000, v23
	v_fmac_f32_e32 v24, v28, v28
	v_fmac_f32_e32 v35, 0xba800000, v23
	v_fmac_f32_e32 v24, v35, v35
	v_fmac_f32_e32 v29, 0xba800000, v23
	v_fmac_f32_e32 v24, v29, v29
	v_fmac_f32_e32 v37, 0xba800000, v23
	v_fmac_f32_e32 v24, v37, v37
	v_fmac_f32_e32 v30, 0xba800000, v23
	v_fmac_f32_e32 v24, v30, v30
	v_fmac_f32_e32 v39, 0xba800000, v23
	v_fmac_f32_e32 v24, v39, v39
	v_fmac_f32_e32 v31, 0xba800000, v23
	v_fmac_f32_e32 v24, v31, v31
	s_nop 1
	v_add_f32_dpp v24, v24, v24 quad_perm:[1,0,3,2] row_mask:0xf bank_mask:0xf bound_ctrl:1
	s_nop 1
	v_add_f32_dpp v24, v24, v24 quad_perm:[2,3,0,1] row_mask:0xf bank_mask:0xf bound_ctrl:1
	s_nop 1
	v_add_f32_dpp v24, v24, v24 row_half_mirror row_mask:0xf bank_mask:0xf bound_ctrl:1
	s_nop 1
	v_add_f32_dpp v24, v24, v24 row_mirror row_mask:0xf bank_mask:0xf bound_ctrl:1
	ds_swizzle_b32 v25, v24 offset:swizzle(SWAP,16)
	s_waitcnt lgkmcnt(0)
	v_add_f32_e32 v24, v24, v25
	v_mov_b32_e32 v25, v24
	s_nop 1
	v_permlane32_swap_b32_e32 v24, v25
	v_add_f32_e32 v24, v24, v25
	v_fmamk_f32 v24, v24, 0x3a800000, v244
	v_cmp_gt_f32_e32 vcc, s81, v24
	v_mul_f32_e32 v25, 0x4f800000, v24
	s_nop 0
	v_cndmask_b32_e32 v24, v24, v25, vcc
	v_sqrt_f32_e32 v25, v24
	s_nop 0
	v_add_u32_e32 v26, -1, v25
	v_fma_f32 v27, -v26, v25, v24
	v_cmp_ge_f32_e64 s[4:5], 0, v27
	v_add_u32_e32 v27, 1, v25
	s_nop 0
	v_cndmask_b32_e64 v26, v25, v26, s[4:5]
	v_fma_f32 v25, -v27, v25, v24
	v_cmp_lt_f32_e64 s[4:5], 0, v25
	s_nop 1
	v_cndmask_b32_e64 v25, v26, v27, s[4:5]
	v_mul_f32_e32 v26, 0x37800000, v25
	v_cndmask_b32_e32 v25, v25, v26, vcc
	v_cmp_class_f32_e32 vcc, v24, v245
	s_nop 1
	v_cndmask_b32_e32 v24, v25, v24, vcc
	v_div_scale_f32 v25, s[4:5], v24, v24, 1.0
	v_rcp_f32_e32 v26, v25
	s_or_b32 s4, s22, 11
	s_ashr_i32 s5, s4, 31
	s_lshl_b64 s[96:97], s[4:5], 11
	v_fma_f32 v27, -v25, v26, 1.0
	v_fmac_f32_e32 v26, v27, v26
	v_div_scale_f32 v27, vcc, 1.0, v24, 1.0
	v_mul_f32_e32 v28, v27, v26
	v_fma_f32 v29, -v25, v28, v27
	v_fmac_f32_e32 v28, v29, v26
	s_add_u32 s4, s6, s96
	v_fma_f32 v25, -v25, v28, v27
	s_addc_u32 s5, s7, s97
	v_div_fmas_f32 v25, v25, v26, v28
	s_waitcnt vmcnt(8)
	v_mov_b32_e32 v26, v152
	v_mov_b32_e32 v27, v153
	v_mov_b32_e32 v28, v154
	v_mov_b32_e32 v29, v155
	v_mov_b32_e32 v30, v156
	v_mov_b32_e32 v31, v157
	v_mov_b32_e32 v32, v158
	v_mov_b32_e32 v33, v159
	v_div_fixup_f32 v24, v25, v24, 1.0
	v_lshlrev_b32_e32 v34, 16, v26
	v_and_b32_e32 v26, 0xffff0000, v26
	v_add_f32_e32 v25, 0, v34
	v_lshlrev_b32_e32 v36, 16, v27
	v_add_f32_e32 v25, v25, v26
	v_and_b32_e32 v27, 0xffff0000, v27
	v_add_f32_e32 v25, v25, v36
	v_lshlrev_b32_e32 v38, 16, v28
	v_add_f32_e32 v25, v25, v27
	v_and_b32_e32 v28, 0xffff0000, v28
	v_add_f32_e32 v25, v25, v38
	v_lshlrev_b32_e32 v40, 16, v29
	v_add_f32_e32 v25, v25, v28
	v_and_b32_e32 v29, 0xffff0000, v29
	v_add_f32_e32 v25, v25, v40
	v_lshlrev_b32_e32 v35, 16, v30
	v_add_f32_e32 v25, v25, v29
	v_and_b32_e32 v30, 0xffff0000, v30
	v_add_f32_e32 v25, v25, v35
	v_lshlrev_b32_e32 v37, 16, v31
	v_add_f32_e32 v25, v25, v30
	v_and_b32_e32 v31, 0xffff0000, v31
	v_add_f32_e32 v25, v25, v37
	v_lshlrev_b32_e32 v39, 16, v32
	v_add_f32_e32 v25, v25, v31
	v_and_b32_e32 v32, 0xffff0000, v32
	v_add_f32_e32 v25, v25, v39
	v_lshlrev_b32_e32 v41, 16, v33
	v_add_f32_e32 v25, v25, v32
	v_and_b32_e32 v33, 0xffff0000, v33
	v_add_f32_e32 v25, v25, v41
	v_add_f32_e32 v25, v25, v33
	s_nop 1
	v_add_f32_dpp v25, v25, v25 quad_perm:[1,0,3,2] row_mask:0xf bank_mask:0xf bound_ctrl:1
	s_nop 1
	v_add_f32_dpp v25, v25, v25 quad_perm:[2,3,0,1] row_mask:0xf bank_mask:0xf bound_ctrl:1
	s_nop 1
	v_add_f32_dpp v25, v25, v25 row_half_mirror row_mask:0xf bank_mask:0xf bound_ctrl:1
	s_nop 1
	v_add_f32_dpp v25, v25, v25 row_mirror row_mask:0xf bank_mask:0xf bound_ctrl:1
	ds_swizzle_b32 v42, v25 offset:swizzle(SWAP,16)
	s_waitcnt lgkmcnt(0)
; __device__ __forceinline__ float bf_lo(unsigned v) { return __uint_as_float(v << 16); }
; __device__ __forceinline__ float bf_hi(unsigned v) { return __uint_as_float(v & 0xffff0000u); }
; __device__ __forceinline__ void sgu_item(int it, const bf16_t* GV, const bf16_t* ZU, const float* sg_, const float* sb_, const float* wsp, const float* bsp, bf16_t* CAT, unsigned char* lds, const int wv) {
;     ...
;         for (int i = 0; i < 16; ++i) { const bf16_t* row = GV + (size_t)(tok0 + 16 * wid + i) * 1024;
;             const u32x4 a = *(const u32x4*)(row + 8 * lane), c = *(const u32x4*)(row + 512 + 8 * lane);
;             float v[16];
; #pragma unroll
;             for (int k = 0; k < 4; ++k) { v[2 * k] = bf_lo(a[k]); v[2 * k + 1] = bf_hi(a[k]); v[8 + 2 * k] = bf_lo(c[k]); v[8 + 2 * k + 1] = bf_hi(c[k]); }
;             float s = 0.f;
; #pragma unroll
;             for (int k = 0; k < 16; ++k) s += v[k];
;             const float mu = wave_sum(s) * (1.0f / 1024.0f); float q = 0.f;
; #pragma unroll
;             for (int k = 0; k < 16; ++k) { const float d = v[k] - mu; q += d * d; }
;             mean[i] = mu; rstd[i] = 1.0f / sqrtf(wave_sum(q) * (1.0f / 1024.0f) + EPS); }
	v_add_f32_e32 v25, v25, v42
	v_mov_b32_e32 v42, v25
	s_nop 1
	v_permlane32_swap_b32_e32 v25, v42
	v_add_f32_e32 v25, v25, v42
	v_fmac_f32_e32 v26, 0xba800000, v25
	v_fmac_f32_e32 v34, 0xba800000, v25
	v_mul_f32_e32 v26, v26, v26
	v_fmac_f32_e32 v26, v34, v34
	v_fmac_f32_e32 v36, 0xba800000, v25
	v_fmac_f32_e32 v26, v36, v36
	v_fmac_f32_e32 v27, 0xba800000, v25
	v_fmac_f32_e32 v26, v27, v27
	v_fmac_f32_e32 v38, 0xba800000, v25
	v_fmac_f32_e32 v26, v38, v38
	v_fmac_f32_e32 v28, 0xba800000, v25
	v_fmac_f32_e32 v26, v28, v28
	v_fmac_f32_e32 v40, 0xba800000, v25
	v_fmac_f32_e32 v26, v40, v40
	v_fmac_f32_e32 v29, 0xba800000, v25
	v_fmac_f32_e32 v26, v29, v29
	v_fmac_f32_e32 v35, 0xba800000, v25
	v_fmac_f32_e32 v26, v35, v35
	v_fmac_f32_e32 v30, 0xba800000, v25
	v_fmac_f32_e32 v26, v30, v30
	v_fmac_f32_e32 v37, 0xba800000, v25
	v_fmac_f32_e32 v26, v37, v37
	v_fmac_f32_e32 v31, 0xba800000, v25
	v_fmac_f32_e32 v26, v31, v31
	v_fmac_f32_e32 v39, 0xba800000, v25
	v_fmac_f32_e32 v26, v39, v39
	v_fmac_f32_e32 v32, 0xba800000, v25
	v_fmac_f32_e32 v26, v32, v32
	v_fmac_f32_e32 v41, 0xba800000, v25
	v_fmac_f32_e32 v26, v41, v41
	v_fmac_f32_e32 v33, 0xba800000, v25
	v_fmac_f32_e32 v26, v33, v33
	s_nop 1
	v_add_f32_dpp v26, v26, v26 quad_perm:[1,0,3,2] row_mask:0xf bank_mask:0xf bound_ctrl:1
	s_nop 1
	v_add_f32_dpp v26, v26, v26 quad_perm:[2,3,0,1] row_mask:0xf bank_mask:0xf bound_ctrl:1
	s_nop 1
	v_add_f32_dpp v26, v26, v26 row_half_mirror row_mask:0xf bank_mask:0xf bound_ctrl:1
	s_nop 1
	v_add_f32_dpp v26, v26, v26 row_mirror row_mask:0xf bank_mask:0xf bound_ctrl:1
	ds_swizzle_b32 v27, v26 offset:swizzle(SWAP,16)
	s_waitcnt lgkmcnt(0)
	v_add_f32_e32 v26, v26, v27
	v_mov_b32_e32 v27, v26
	s_nop 1
	v_permlane32_swap_b32_e32 v26, v27
	v_add_f32_e32 v26, v26, v27
	v_fmamk_f32 v26, v26, 0x3a800000, v244
	v_cmp_gt_f32_e32 vcc, s81, v26
	v_mul_f32_e32 v27, 0x4f800000, v26
	s_nop 0
	v_cndmask_b32_e32 v26, v26, v27, vcc
	v_sqrt_f32_e32 v27, v26
	s_nop 0
	v_add_u32_e32 v28, -1, v27
	v_fma_f32 v29, -v28, v27, v26
	v_cmp_ge_f32_e64 s[4:5], 0, v29
	v_add_u32_e32 v29, 1, v27
	s_nop 0
	v_cndmask_b32_e64 v28, v27, v28, s[4:5]
	v_fma_f32 v27, -v29, v27, v26
	v_cmp_lt_f32_e64 s[4:5], 0, v27
	s_nop 1
	v_cndmask_b32_e64 v27, v28, v29, s[4:5]
	v_mul_f32_e32 v28, 0x37800000, v27
	v_cndmask_b32_e32 v27, v27, v28, vcc
	v_cmp_class_f32_e32 vcc, v26, v245
	s_nop 1
	v_cndmask_b32_e32 v26, v27, v26, vcc
	v_div_scale_f32 v27, s[4:5], v26, v26, 1.0
	v_rcp_f32_e32 v28, v27
	s_or_b32 s4, s22, 12
	s_ashr_i32 s5, s4, 31
	s_lshl_b64 s[94:95], s[4:5], 11
	v_fma_f32 v29, -v27, v28, 1.0
	v_fmac_f32_e32 v28, v29, v28
	v_div_scale_f32 v29, vcc, 1.0, v26, 1.0
	v_mul_f32_e32 v30, v29, v28
	v_fma_f32 v31, -v27, v30, v29
	v_fmac_f32_e32 v30, v31, v28
	s_add_u32 s4, s6, s94
	v_fma_f32 v27, -v27, v30, v29
	s_addc_u32 s5, s7, s95
	v_div_fmas_f32 v27, v27, v28, v30
	s_waitcnt vmcnt(6)
	v_mov_b32_e32 v28, v160
	v_mov_b32_e32 v29, v161
	v_mov_b32_e32 v30, v162
	v_mov_b32_e32 v31, v163
	v_mov_b32_e32 v32, v164
	v_mov_b32_e32 v33, v165
	v_mov_b32_e32 v34, v166
	v_mov_b32_e32 v35, v167
	v_div_fixup_f32 v26, v27, v26, 1.0
	v_lshlrev_b32_e32 v36, 16, v28
	v_and_b32_e32 v28, 0xffff0000, v28
	v_add_f32_e32 v27, 0, v36
	v_lshlrev_b32_e32 v38, 16, v29
	v_add_f32_e32 v27, v27, v28
	v_and_b32_e32 v29, 0xffff0000, v29
	v_add_f32_e32 v27, v27, v38
	v_lshlrev_b32_e32 v40, 16, v30
	v_add_f32_e32 v27, v27, v29
	v_and_b32_e32 v30, 0xffff0000, v30
	v_add_f32_e32 v27, v27, v40
	v_lshlrev_b32_e32 v42, 16, v31
	v_add_f32_e32 v27, v27, v30
	v_and_b32_e32 v31, 0xffff0000, v31
	v_add_f32_e32 v27, v27, v42
	v_lshlrev_b32_e32 v37, 16, v32
	v_add_f32_e32 v27, v27, v31
	v_and_b32_e32 v32, 0xffff0000, v32
	v_add_f32_e32 v27, v27, v37
	v_lshlrev_b32_e32 v39, 16, v33
	v_add_f32_e32 v27, v27, v32
	v_and_b32_e32 v33, 0xffff0000, v33
	v_add_f32_e32 v27, v27, v39
	v_lshlrev_b32_e32 v41, 16, v34
	v_add_f32_e32 v27, v27, v33
	v_and_b32_e32 v34, 0xffff0000, v34
	v_add_f32_e32 v27, v27, v41
	v_lshlrev_b32_e32 v43, 16, v35
	v_add_f32_e32 v27, v27, v34
	v_and_b32_e32 v35, 0xffff0000, v35
	v_add_f32_e32 v27, v27, v43
	v_add_f32_e32 v27, v27, v35
	s_nop 1
	v_add_f32_dpp v27, v27, v27 quad_perm:[1,0,3,2] row_mask:0xf bank_mask:0xf bound_ctrl:1
	s_nop 1
	v_add_f32_dpp v27, v27, v27 quad_perm:[2,3,0,1] row_mask:0xf bank_mask:0xf bound_ctrl:1
	s_nop 1
	v_add_f32_dpp v27, v27, v27 row_half_mirror row_mask:0xf bank_mask:0xf bound_ctrl:1
	s_nop 1
	v_add_f32_dpp v27, v27, v27 row_mirror row_mask:0xf bank_mask:0xf bound_ctrl:1
	ds_swizzle_b32 v44, v27 offset:swizzle(SWAP,16)
	s_waitcnt lgkmcnt(0)
	v_add_f32_e32 v27, v27, v44
	v_mov_b32_e32 v44, v27
	s_nop 1
	v_permlane32_swap_b32_e32 v27, v44
	v_add_f32_e32 v27, v27, v44
	v_fmac_f32_e32 v28, 0xba800000, v27
	v_fmac_f32_e32 v36, 0xba800000, v27
	v_mul_f32_e32 v28, v28, v28
	v_fmac_f32_e32 v28, v36, v36
	v_fmac_f32_e32 v38, 0xba800000, v27
	v_fmac_f32_e32 v28, v38, v38
	v_fmac_f32_e32 v29, 0xba800000, v27
	v_fmac_f32_e32 v28, v29, v29
	v_fmac_f32_e32 v40, 0xba800000, v27
	v_fmac_f32_e32 v28, v40, v40
	v_fmac_f32_e32 v30, 0xba800000, v27
	v_fmac_f32_e32 v28, v30, v30
	v_fmac_f32_e32 v42, 0xba800000, v27
	v_fmac_f32_e32 v28, v42, v42
	v_fmac_f32_e32 v31, 0xba800000, v27
	v_fmac_f32_e32 v28, v31, v31
	v_fmac_f32_e32 v37, 0xba800000, v27
	v_fmac_f32_e32 v28, v37, v37
	v_fmac_f32_e32 v32, 0xba800000, v27
	v_fmac_f32_e32 v28, v32, v32
	v_fmac_f32_e32 v39, 0xba800000, v27
	v_fmac_f32_e32 v28, v39, v39
	v_fmac_f32_e32 v33, 0xba800000, v27
	v_fmac_f32_e32 v28, v33, v33
	v_fmac_f32_e32 v41, 0xba800000, v27
	v_fmac_f32_e32 v28, v41, v41
	v_fmac_f32_e32 v34, 0xba800000, v27
	v_fmac_f32_e32 v28, v34, v34
	v_fmac_f32_e32 v43, 0xba800000, v27
	v_fmac_f32_e32 v28, v43, v43
	v_fmac_f32_e32 v35, 0xba800000, v27
	v_fmac_f32_e32 v28, v35, v35
	s_nop 1
	v_add_f32_dpp v28, v28, v28 quad_perm:[1,0,3,2] row_mask:0xf bank_mask:0xf bound_ctrl:1
	s_nop 1
	v_add_f32_dpp v28, v28, v28 quad_perm:[2,3,0,1] row_mask:0xf bank_mask:0xf bound_ctrl:1
	s_nop 1
	v_add_f32_dpp v28, v28, v28 row_half_mirror row_mask:0xf bank_mask:0xf bound_ctrl:1
	s_nop 1
	v_add_f32_dpp v28, v28, v28 row_mirror row_mask:0xf bank_mask:0xf bound_ctrl:1
	ds_swizzle_b32 v29, v28 offset:swizzle(SWAP,16)
	s_waitcnt lgkmcnt(0)
; __device__ __forceinline__ float bf_lo(unsigned v) { return __uint_as_float(v << 16); }
; __device__ __forceinline__ float bf_hi(unsigned v) { return __uint_as_float(v & 0xffff0000u); }
; __device__ __forceinline__ void sgu_item(int it, const bf16_t* GV, const bf16_t* ZU, const float* sg_, const float* sb_, const float* wsp, const float* bsp, bf16_t* CAT, unsigned char* lds, const int wv) {
;     ...
;         for (int i = 0; i < 16; ++i) { const bf16_t* row = GV + (size_t)(tok0 + 16 * wid + i) * 1024;
;             const u32x4 a = *(const u32x4*)(row + 8 * lane), c = *(const u32x4*)(row + 512 + 8 * lane);
;             float v[16];
; #pragma unroll
;             for (int k = 0; k < 4; ++k) { v[2 * k] = bf_lo(a[k]); v[2 * k + 1] = bf_hi(a[k]); v[8 + 2 * k] = bf_lo(c[k]); v[8 + 2 * k + 1] = bf_hi(c[k]); }
;             float s = 0.f;
; #pragma unroll
;             for (int k = 0; k < 16; ++k) s += v[k];
;             const float mu = wave_sum(s) * (1.0f / 1024.0f); float q = 0.f;
; #pragma unroll
;             for (int k = 0; k < 16; ++k) { const float d = v[k] - mu; q += d * d; }
;             mean[i] = mu; rstd[i] = 1.0f / sqrtf(wave_sum(q) * (1.0f / 1024.0f) + EPS); }
	v_add_f32_e32 v28, v28, v29
	v_mov_b32_e32 v29, v28
	s_nop 1
	v_permlane32_swap_b32_e32 v28, v29
	v_add_f32_e32 v28, v28, v29
	v_fmamk_f32 v28, v28, 0x3a800000, v244
	v_cmp_gt_f32_e32 vcc, s81, v28
	v_mul_f32_e32 v29, 0x4f800000, v28
	s_nop 0
	v_cndmask_b32_e32 v28, v28, v29, vcc
	v_sqrt_f32_e32 v29, v28
	s_nop 0
	v_add_u32_e32 v30, -1, v29
	v_fma_f32 v31, -v30, v29, v28
	v_cmp_ge_f32_e64 s[4:5], 0, v31
	v_add_u32_e32 v31, 1, v29
	s_nop 0
	v_cndmask_b32_e64 v30, v29, v30, s[4:5]
	v_fma_f32 v29, -v31, v29, v28
	v_cmp_lt_f32_e64 s[4:5], 0, v29
	s_nop 1
	v_cndmask_b32_e64 v29, v30, v31, s[4:5]
	v_mul_f32_e32 v30, 0x37800000, v29
	v_cndmask_b32_e32 v29, v29, v30, vcc
	v_cmp_class_f32_e32 vcc, v28, v245
	s_nop 1
	v_cndmask_b32_e32 v28, v29, v28, vcc
	v_div_scale_f32 v29, s[4:5], v28, v28, 1.0
	v_rcp_f32_e32 v30, v29
	s_or_b32 s4, s22, 13
	s_ashr_i32 s5, s4, 31
	s_lshl_b64 s[88:89], s[4:5], 11
	v_fma_f32 v31, -v29, v30, 1.0
	v_fmac_f32_e32 v30, v31, v30
	v_div_scale_f32 v31, vcc, 1.0, v28, 1.0
	v_mul_f32_e32 v32, v31, v30
	v_fma_f32 v33, -v29, v32, v31
	v_fmac_f32_e32 v32, v33, v30
	v_fma_f32 v29, -v29, v32, v31
	s_add_u32 s4, s6, s88
	v_div_fmas_f32 v29, v29, v30, v32
	s_addc_u32 s5, s7, s89
	v_div_fixup_f32 v36, v29, v28, 1.0
	s_waitcnt vmcnt(4)
	v_mov_b32_e32 v28, v168
	v_mov_b32_e32 v29, v169
	v_mov_b32_e32 v30, v170
	v_mov_b32_e32 v31, v171
	v_mov_b32_e32 v32, v172
	v_mov_b32_e32 v33, v173
	v_mov_b32_e32 v34, v174
	v_mov_b32_e32 v35, v175
	v_lshlrev_b32_e32 v37, 16, v28
	v_and_b32_e32 v28, 0xffff0000, v28
	v_add_f32_e32 v45, 0, v37
	v_lshlrev_b32_e32 v39, 16, v29
	v_add_f32_e32 v45, v45, v28
	v_and_b32_e32 v29, 0xffff0000, v29
	v_add_f32_e32 v45, v45, v39
	v_lshlrev_b32_e32 v41, 16, v30
	v_add_f32_e32 v45, v45, v29
	v_and_b32_e32 v30, 0xffff0000, v30
	v_add_f32_e32 v45, v45, v41
	v_lshlrev_b32_e32 v43, 16, v31
	v_add_f32_e32 v45, v45, v30
	v_and_b32_e32 v31, 0xffff0000, v31
	v_add_f32_e32 v45, v45, v43
	v_lshlrev_b32_e32 v38, 16, v32
	v_add_f32_e32 v45, v45, v31
	v_and_b32_e32 v32, 0xffff0000, v32
	v_add_f32_e32 v45, v45, v38
	v_lshlrev_b32_e32 v40, 16, v33
	v_add_f32_e32 v45, v45, v32
	v_and_b32_e32 v33, 0xffff0000, v33
	v_add_f32_e32 v45, v45, v40
	v_lshlrev_b32_e32 v42, 16, v34
	v_add_f32_e32 v45, v45, v33
	v_and_b32_e32 v34, 0xffff0000, v34
	v_add_f32_e32 v45, v45, v42
	v_lshlrev_b32_e32 v44, 16, v35
	v_add_f32_e32 v45, v45, v34
	v_and_b32_e32 v35, 0xffff0000, v35
	v_add_f32_e32 v45, v45, v44
	v_add_f32_e32 v45, v45, v35
	s_nop 1
	v_add_f32_dpp v45, v45, v45 quad_perm:[1,0,3,2] row_mask:0xf bank_mask:0xf bound_ctrl:1
	s_nop 1
	v_add_f32_dpp v45, v45, v45 quad_perm:[2,3,0,1] row_mask:0xf bank_mask:0xf bound_ctrl:1
	s_nop 1
	v_add_f32_dpp v45, v45, v45 row_half_mirror row_mask:0xf bank_mask:0xf bound_ctrl:1
	s_nop 1
	v_add_f32_dpp v45, v45, v45 row_mirror row_mask:0xf bank_mask:0xf bound_ctrl:1
	ds_swizzle_b32 v46, v45 offset:swizzle(SWAP,16)
	s_waitcnt lgkmcnt(0)
	v_add_f32_e32 v45, v45, v46
	v_mov_b32_e32 v46, v45
	s_nop 1
	v_permlane32_swap_b32_e32 v45, v46
	v_add_f32_e32 v45, v45, v46
	v_fmac_f32_e32 v28, 0xba800000, v45
	v_fmac_f32_e32 v37, 0xba800000, v45
	v_mul_f32_e32 v28, v28, v28
	v_fmac_f32_e32 v28, v37, v37
	v_fmac_f32_e32 v39, 0xba800000, v45
	v_fmac_f32_e32 v28, v39, v39
	v_fmac_f32_e32 v29, 0xba800000, v45
	v_fmac_f32_e32 v28, v29, v29
	v_fmac_f32_e32 v41, 0xba800000, v45
	v_fmac_f32_e32 v28, v41, v41
	v_fmac_f32_e32 v30, 0xba800000, v45
	v_fmac_f32_e32 v28, v30, v30
	v_fmac_f32_e32 v43, 0xba800000, v45
	v_fmac_f32_e32 v28, v43, v43
	v_fmac_f32_e32 v31, 0xba800000, v45
	v_fmac_f32_e32 v28, v31, v31
	v_fmac_f32_e32 v38, 0xba800000, v45
	v_fmac_f32_e32 v28, v38, v38
	v_fmac_f32_e32 v32, 0xba800000, v45
	v_fmac_f32_e32 v28, v32, v32
	v_fmac_f32_e32 v40, 0xba800000, v45
	v_fmac_f32_e32 v28, v40, v40
	v_fmac_f32_e32 v33, 0xba800000, v45
	v_fmac_f32_e32 v28, v33, v33
	v_fmac_f32_e32 v42, 0xba800000, v45
	v_fmac_f32_e32 v28, v42, v42
	v_fmac_f32_e32 v34, 0xba800000, v45
	v_fmac_f32_e32 v28, v34, v34
	v_fmac_f32_e32 v44, 0xba800000, v45
	v_fmac_f32_e32 v28, v44, v44
	v_fmac_f32_e32 v35, 0xba800000, v45
	v_fmac_f32_e32 v28, v35, v35
	s_nop 1
	v_add_f32_dpp v28, v28, v28 quad_perm:[1,0,3,2] row_mask:0xf bank_mask:0xf bound_ctrl:1
	s_nop 1
	v_add_f32_dpp v28, v28, v28 quad_perm:[2,3,0,1] row_mask:0xf bank_mask:0xf bound_ctrl:1
	s_nop 1
	v_add_f32_dpp v28, v28, v28 row_half_mirror row_mask:0xf bank_mask:0xf bound_ctrl:1
	s_nop 1
	v_add_f32_dpp v28, v28, v28 row_mirror row_mask:0xf bank_mask:0xf bound_ctrl:1
	ds_swizzle_b32 v29, v28 offset:swizzle(SWAP,16)
	s_waitcnt lgkmcnt(0)
	v_add_f32_e32 v28, v28, v29
	v_mov_b32_e32 v29, v28
	s_nop 1
	v_permlane32_swap_b32_e32 v28, v29
	v_add_f32_e32 v28, v28, v29
	v_fmamk_f32 v28, v28, 0x3a800000, v244
	v_cmp_gt_f32_e32 vcc, s81, v28
	v_mul_f32_e32 v29, 0x4f800000, v28
	s_nop 0
	v_cndmask_b32_e32 v28, v28, v29, vcc
	v_sqrt_f32_e32 v29, v28
	s_nop 0
	v_add_u32_e32 v30, -1, v29
	v_fma_f32 v31, -v30, v29, v28
	v_cmp_ge_f32_e64 s[4:5], 0, v31
	v_add_u32_e32 v31, 1, v29
	s_nop 0
	v_cndmask_b32_e64 v30, v29, v30, s[4:5]
	v_fma_f32 v29, -v31, v29, v28
	v_cmp_lt_f32_e64 s[4:5], 0, v29
	s_nop 1
	v_cndmask_b32_e64 v29, v30, v31, s[4:5]
	v_mul_f32_e32 v30, 0x37800000, v29
	v_cndmask_b32_e32 v29, v29, v30, vcc
	v_cmp_class_f32_e32 vcc, v28, v245
	s_nop 1
	v_cndmask_b32_e32 v28, v29, v28, vcc
	v_div_scale_f32 v29, s[4:5], v28, v28, 1.0
	v_rcp_f32_e32 v30, v29
	s_or_b32 s4, s22, 14
	s_ashr_i32 s5, s4, 31
	s_lshl_b64 s[86:87], s[4:5], 11
	v_fma_f32 v31, -v29, v30, 1.0
	v_fmac_f32_e32 v30, v31, v30
	v_div_scale_f32 v31, vcc, 1.0, v28, 1.0
	v_mul_f32_e32 v32, v31, v30
	v_fma_f32 v33, -v29, v32, v31
	v_fmac_f32_e32 v32, v33, v30
	v_fma_f32 v29, -v29, v32, v31
	s_add_u32 s4, s6, s86
	v_div_fmas_f32 v29, v29, v30, v32
	s_addc_u32 s5, s7, s87
	v_div_fixup_f32 v37, v29, v28, 1.0
	s_waitcnt vmcnt(2)
; __device__ __forceinline__ float bf_lo(unsigned v) { return __uint_as_float(v << 16); }
; __device__ __forceinline__ float bf_hi(unsigned v) { return __uint_as_float(v & 0xffff0000u); }
; __device__ __forceinline__ void sgu_item(int it, const bf16_t* GV, const bf16_t* ZU, const float* sg_, const float* sb_, const float* wsp, const float* bsp, bf16_t* CAT, unsigned char* lds, const int wv) {
;     ...
;         for (int i = 0; i < 16; ++i) { const bf16_t* row = GV + (size_t)(tok0 + 16 * wid + i) * 1024;
;             const u32x4 a = *(const u32x4*)(row + 8 * lane), c = *(const u32x4*)(row + 512 + 8 * lane);
;             float v[16];
; #pragma unroll
;             for (int k = 0; k < 4; ++k) { v[2 * k] = bf_lo(a[k]); v[2 * k + 1] = bf_hi(a[k]); v[8 + 2 * k] = bf_lo(c[k]); v[8 + 2 * k + 1] = bf_hi(c[k]); }
;             float s = 0.f;
; #pragma unroll
;             for (int k = 0; k < 16; ++k) s += v[k];
;             const float mu = wave_sum(s) * (1.0f / 1024.0f); float q = 0.f;
; #pragma unroll
;             for (int k = 0; k < 16; ++k) { const float d = v[k] - mu; q += d * d; }
;             mean[i] = mu; rstd[i] = 1.0f / sqrtf(wave_sum(q) * (1.0f / 1024.0f) + EPS); }
	v_mov_b32_e32 v28, v176
	v_mov_b32_e32 v29, v177
	v_mov_b32_e32 v30, v178
	v_mov_b32_e32 v31, v179
	v_mov_b32_e32 v32, v180
	v_mov_b32_e32 v33, v181
	v_mov_b32_e32 v34, v182
	v_mov_b32_e32 v35, v183
	v_lshlrev_b32_e32 v38, 16, v28
	v_and_b32_e32 v28, 0xffff0000, v28
	v_add_f32_e32 v47, 0, v38
	v_lshlrev_b32_e32 v40, 16, v29
	v_add_f32_e32 v47, v47, v28
	v_and_b32_e32 v29, 0xffff0000, v29
	v_add_f32_e32 v47, v47, v40
	v_lshlrev_b32_e32 v42, 16, v30
	v_add_f32_e32 v47, v47, v29
	v_and_b32_e32 v30, 0xffff0000, v30
	v_add_f32_e32 v47, v47, v42
	v_lshlrev_b32_e32 v44, 16, v31
	v_add_f32_e32 v47, v47, v30
	v_and_b32_e32 v31, 0xffff0000, v31
	v_add_f32_e32 v47, v47, v44
	v_lshlrev_b32_e32 v39, 16, v32
	v_add_f32_e32 v47, v47, v31
	v_and_b32_e32 v32, 0xffff0000, v32
	v_add_f32_e32 v47, v47, v39
	v_lshlrev_b32_e32 v41, 16, v33
	v_add_f32_e32 v47, v47, v32
	v_and_b32_e32 v33, 0xffff0000, v33
	v_add_f32_e32 v47, v47, v41
	v_lshlrev_b32_e32 v43, 16, v34
	v_add_f32_e32 v47, v47, v33
	v_and_b32_e32 v34, 0xffff0000, v34
	v_add_f32_e32 v47, v47, v43
	v_lshlrev_b32_e32 v46, 16, v35
	v_add_f32_e32 v47, v47, v34
	v_and_b32_e32 v35, 0xffff0000, v35
	v_add_f32_e32 v47, v47, v46
	v_add_f32_e32 v47, v47, v35
	s_nop 1
	v_add_f32_dpp v47, v47, v47 quad_perm:[1,0,3,2] row_mask:0xf bank_mask:0xf bound_ctrl:1
	s_nop 1
	v_add_f32_dpp v47, v47, v47 quad_perm:[2,3,0,1] row_mask:0xf bank_mask:0xf bound_ctrl:1
	s_nop 1
	v_add_f32_dpp v47, v47, v47 row_half_mirror row_mask:0xf bank_mask:0xf bound_ctrl:1
	s_nop 1
	v_add_f32_dpp v47, v47, v47 row_mirror row_mask:0xf bank_mask:0xf bound_ctrl:1
	ds_swizzle_b32 v48, v47 offset:swizzle(SWAP,16)
	s_waitcnt lgkmcnt(0)
	v_add_f32_e32 v47, v47, v48
	v_mov_b32_e32 v48, v47
	s_nop 1
	v_permlane32_swap_b32_e32 v47, v48
	v_add_f32_e32 v47, v47, v48
	v_fmac_f32_e32 v28, 0xba800000, v47
	v_fmac_f32_e32 v38, 0xba800000, v47
	v_mul_f32_e32 v28, v28, v28
	v_fmac_f32_e32 v28, v38, v38
	v_fmac_f32_e32 v40, 0xba800000, v47
	v_fmac_f32_e32 v28, v40, v40
	v_fmac_f32_e32 v29, 0xba800000, v47
	v_fmac_f32_e32 v28, v29, v29
	v_fmac_f32_e32 v42, 0xba800000, v47
	v_fmac_f32_e32 v28, v42, v42
	v_fmac_f32_e32 v30, 0xba800000, v47
	v_fmac_f32_e32 v28, v30, v30
	v_fmac_f32_e32 v44, 0xba800000, v47
	v_fmac_f32_e32 v28, v44, v44
	v_fmac_f32_e32 v31, 0xba800000, v47
	v_fmac_f32_e32 v28, v31, v31
	v_fmac_f32_e32 v39, 0xba800000, v47
	v_fmac_f32_e32 v28, v39, v39
	v_fmac_f32_e32 v32, 0xba800000, v47
	v_fmac_f32_e32 v28, v32, v32
	v_fmac_f32_e32 v41, 0xba800000, v47
	v_fmac_f32_e32 v28, v41, v41
	v_fmac_f32_e32 v33, 0xba800000, v47
	v_fmac_f32_e32 v28, v33, v33
	v_fmac_f32_e32 v43, 0xba800000, v47
	v_fmac_f32_e32 v28, v43, v43
	v_fmac_f32_e32 v34, 0xba800000, v47
	v_fmac_f32_e32 v28, v34, v34
	v_fmac_f32_e32 v46, 0xba800000, v47
	v_fmac_f32_e32 v28, v46, v46
	v_fmac_f32_e32 v35, 0xba800000, v47
	v_fmac_f32_e32 v28, v35, v35
	s_nop 1
	v_add_f32_dpp v28, v28, v28 quad_perm:[1,0,3,2] row_mask:0xf bank_mask:0xf bound_ctrl:1
	s_nop 1
	v_add_f32_dpp v28, v28, v28 quad_perm:[2,3,0,1] row_mask:0xf bank_mask:0xf bound_ctrl:1
	s_nop 1
	v_add_f32_dpp v28, v28, v28 row_half_mirror row_mask:0xf bank_mask:0xf bound_ctrl:1
	s_nop 1
	v_add_f32_dpp v28, v28, v28 row_mirror row_mask:0xf bank_mask:0xf bound_ctrl:1
	ds_swizzle_b32 v29, v28 offset:swizzle(SWAP,16)
	s_waitcnt lgkmcnt(0)
	v_add_f32_e32 v28, v28, v29
	v_mov_b32_e32 v29, v28
	s_nop 1
	v_permlane32_swap_b32_e32 v28, v29
	v_add_f32_e32 v28, v28, v29
	v_fmamk_f32 v28, v28, 0x3a800000, v244
	v_cmp_gt_f32_e32 vcc, s81, v28
	v_mul_f32_e32 v29, 0x4f800000, v28
	s_nop 0
	v_cndmask_b32_e32 v28, v28, v29, vcc
	v_sqrt_f32_e32 v29, v28
	s_nop 0
	v_add_u32_e32 v30, -1, v29
	v_fma_f32 v31, -v30, v29, v28
	v_cmp_ge_f32_e64 s[4:5], 0, v31
	v_add_u32_e32 v31, 1, v29
	s_nop 0
	v_cndmask_b32_e64 v30, v29, v30, s[4:5]
	v_fma_f32 v29, -v31, v29, v28
	v_cmp_lt_f32_e64 s[4:5], 0, v29
	s_nop 1
	v_cndmask_b32_e64 v29, v30, v31, s[4:5]
	v_mul_f32_e32 v30, 0x37800000, v29
	v_cndmask_b32_e32 v29, v29, v30, vcc
	v_cmp_class_f32_e32 vcc, v28, v245
	s_nop 1
	v_cndmask_b32_e32 v28, v29, v28, vcc
	v_div_scale_f32 v29, s[4:5], v28, v28, 1.0
	v_rcp_f32_e32 v30, v29
	s_or_b32 s4, s22, 15
	s_ashr_i32 s5, s4, 31
	s_lshl_b64 s[22:23], s[4:5], 11
	v_fma_f32 v31, -v29, v30, 1.0
	v_fmac_f32_e32 v30, v31, v30
	v_div_scale_f32 v31, vcc, 1.0, v28, 1.0
	v_mul_f32_e32 v32, v31, v30
	v_fma_f32 v33, -v29, v32, v31
	v_fmac_f32_e32 v32, v33, v30
	v_fma_f32 v29, -v29, v32, v31
	s_add_u32 s4, s6, s22
	v_div_fmas_f32 v29, v29, v30, v32
	s_addc_u32 s5, s7, s23
	v_div_fixup_f32 v38, v29, v28, 1.0
	s_waitcnt vmcnt(0)
	v_mov_b32_e32 v28, v184
	v_mov_b32_e32 v29, v185
	v_mov_b32_e32 v30, v186
	v_mov_b32_e32 v31, v187
	v_mov_b32_e32 v32, v188
	v_mov_b32_e32 v33, v189
	v_mov_b32_e32 v34, v190
	v_mov_b32_e32 v35, v191
	s_and_b32 s38, s8, 0x380
	s_lshl_b32 s1, s9, 5
	s_add_i32 s1, s1, 0
	s_add_i32 s8, s8, s65
	v_lshlrev_b32_e32 v3, 16, v28
	v_and_b32_e32 v28, 0xffff0000, v28
	v_add_f32_e32 v48, 0, v3
	v_lshlrev_b32_e32 v40, 16, v29
	v_add_f32_e32 v48, v48, v28
	v_and_b32_e32 v29, 0xffff0000, v29
	v_add_f32_e32 v48, v48, v40
	v_lshlrev_b32_e32 v42, 16, v30
	v_add_f32_e32 v48, v48, v29
	v_and_b32_e32 v30, 0xffff0000, v30
	v_add_f32_e32 v48, v48, v42
	v_lshlrev_b32_e32 v44, 16, v31
	v_add_f32_e32 v48, v48, v30
	v_and_b32_e32 v31, 0xffff0000, v31
	v_add_f32_e32 v48, v48, v44
	v_lshlrev_b32_e32 v39, 16, v32
	v_add_f32_e32 v48, v48, v31
	v_and_b32_e32 v32, 0xffff0000, v32
	v_add_f32_e32 v48, v48, v39
	v_lshlrev_b32_e32 v41, 16, v33
	v_add_f32_e32 v48, v48, v32
	v_and_b32_e32 v33, 0xffff0000, v33
	v_add_f32_e32 v48, v48, v41
	v_lshlrev_b32_e32 v43, 16, v34
	v_add_f32_e32 v48, v48, v33
	v_and_b32_e32 v34, 0xffff0000, v34
	v_add_f32_e32 v48, v48, v43
	v_lshlrev_b32_e32 v46, 16, v35
	v_add_f32_e32 v48, v48, v34
	v_and_b32_e32 v35, 0xffff0000, v35
	v_add_f32_e32 v48, v48, v46
	v_add_f32_e32 v48, v48, v35
	s_nop 1
	v_add_f32_dpp v48, v48, v48 quad_perm:[1,0,3,2] row_mask:0xf bank_mask:0xf bound_ctrl:1
	s_nop 1
	v_add_f32_dpp v48, v48, v48 quad_perm:[2,3,0,1] row_mask:0xf bank_mask:0xf bound_ctrl:1
	s_nop 1
	v_add_f32_dpp v48, v48, v48 row_half_mirror row_mask:0xf bank_mask:0xf bound_ctrl:1
	s_nop 1
	v_add_f32_dpp v48, v48, v48 row_mirror row_mask:0xf bank_mask:0xf bound_ctrl:1
	ds_swizzle_b32 v49, v48 offset:swizzle(SWAP,16)
	s_waitcnt lgkmcnt(0)
; __device__ __forceinline__ float bf_lo(unsigned v) { return __uint_as_float(v << 16); }
; __device__ __forceinline__ float bf_hi(unsigned v) { return __uint_as_float(v & 0xffff0000u); }
; __device__ __forceinline__ void sgu_item(int it, const bf16_t* GV, const bf16_t* ZU, const float* sg_, const float* sb_, const float* wsp, const float* bsp, bf16_t* CAT, unsigned char* lds, const int wv) {
;     ...
;             const float mu = wave_sum(s) * (1.0f / 1024.0f); float q = 0.f;
; #pragma unroll
;             for (int k = 0; k < 16; ++k) { const float d = v[k] - mu; q += d * d; }
;             mean[i] = mu; rstd[i] = 1.0f / sqrtf(wave_sum(q) * (1.0f / 1024.0f) + EPS); }
;         const int c0 = g * 128 + 2 * lane;
;         const f32x2 sgv = *(const f32x2*)(sg_ + c0), sbv = *(const f32x2*)(sb_ + c0);
;         float z0[16], z1[16];
; #pragma unroll
;         for (int i = 0; i < 16; ++i) { const unsigned v = *(const unsigned*)(GV + (size_t)(tok0 + 16 * wid + i) * 1024 + c0);
;             z0[i] = (bf_lo(v) - mean[i]) * rstd[i] * sgv.x + sbv.x; z1[i] = (bf_hi(v) - mean[i]) * rstd[i] * sgv.y + sbv.y; }
	v_add_f32_e32 v48, v48, v49
	v_mov_b32_e32 v49, v48
	s_nop 1
	v_permlane32_swap_b32_e32 v48, v49
	v_add_f32_e32 v48, v48, v49
	v_fmac_f32_e32 v28, 0xba800000, v48
	v_fmac_f32_e32 v3, 0xba800000, v48
	v_mul_f32_e32 v28, v28, v28
	v_fmac_f32_e32 v28, v3, v3
	v_fmac_f32_e32 v40, 0xba800000, v48
	v_fmac_f32_e32 v28, v40, v40
	v_fmac_f32_e32 v29, 0xba800000, v48
	v_fmac_f32_e32 v28, v29, v29
	v_fmac_f32_e32 v42, 0xba800000, v48
	v_fmac_f32_e32 v28, v42, v42
	v_fmac_f32_e32 v30, 0xba800000, v48
	v_fmac_f32_e32 v28, v30, v30
	v_fmac_f32_e32 v44, 0xba800000, v48
	v_fmac_f32_e32 v28, v44, v44
	v_fmac_f32_e32 v31, 0xba800000, v48
	v_fmac_f32_e32 v28, v31, v31
	v_fmac_f32_e32 v39, 0xba800000, v48
	v_fmac_f32_e32 v28, v39, v39
	v_fmac_f32_e32 v32, 0xba800000, v48
	v_fmac_f32_e32 v28, v32, v32
	v_fmac_f32_e32 v41, 0xba800000, v48
	v_fmac_f32_e32 v28, v41, v41
	v_fmac_f32_e32 v33, 0xba800000, v48
	v_fmac_f32_e32 v28, v33, v33
	v_fmac_f32_e32 v43, 0xba800000, v48
	v_fmac_f32_e32 v28, v43, v43
	v_fmac_f32_e32 v34, 0xba800000, v48
	v_fmac_f32_e32 v28, v34, v34
	v_fmac_f32_e32 v46, 0xba800000, v48
	v_fmac_f32_e32 v28, v46, v46
	v_fmac_f32_e32 v35, 0xba800000, v48
	v_fmac_f32_e32 v28, v35, v35
	v_lshlrev_b32_e32 v39, 1, v0
	v_or_b32_e32 v0, s38, v39
	v_add_f32_dpp v3, v28, v28 quad_perm:[1,0,3,2] row_mask:0xf bank_mask:0xf bound_ctrl:1
	v_lshlrev_b32_e32 v210, 1, v0
	s_nop 0
	v_add_f32_dpp v3, v3, v3 quad_perm:[2,3,0,1] row_mask:0xf bank_mask:0xf bound_ctrl:1
	s_nop 1
	v_add_f32_dpp v3, v3, v3 row_half_mirror row_mask:0xf bank_mask:0xf bound_ctrl:1
	s_nop 1
	v_add_f32_dpp v3, v3, v3 row_mirror row_mask:0xf bank_mask:0xf bound_ctrl:1
	ds_swizzle_b32 v28, v3 offset:swizzle(SWAP,16)
	s_waitcnt lgkmcnt(0)
	v_add_f32_e32 v3, v3, v28
	v_mov_b32_e32 v28, v3
	s_nop 1
	v_permlane32_swap_b32_e32 v3, v28
	v_add_f32_e32 v3, v3, v28
	v_fmamk_f32 v3, v3, 0x3a800000, v244
	v_cmp_gt_f32_e32 vcc, s81, v3
	v_mul_f32_e32 v28, 0x4f800000, v3
	s_nop 0
	v_cndmask_b32_e32 v3, v3, v28, vcc
	v_sqrt_f32_e32 v28, v3
	s_nop 0
	v_add_u32_e32 v29, -1, v28
	v_fma_f32 v30, -v29, v28, v3
	v_cmp_ge_f32_e64 s[4:5], 0, v30
	v_add_u32_e32 v30, 1, v28
	s_nop 0
	v_cndmask_b32_e64 v29, v28, v29, s[4:5]
	v_fma_f32 v28, -v30, v28, v3
	v_cmp_lt_f32_e64 s[4:5], 0, v28
	s_nop 1
	v_cndmask_b32_e64 v28, v29, v30, s[4:5]
	v_mul_f32_e32 v29, 0x37800000, v28
	v_cndmask_b32_e32 v28, v28, v29, vcc
	v_cmp_class_f32_e32 vcc, v3, v245
	s_nop 1
	v_cndmask_b32_e32 v3, v28, v3, vcc
	v_div_scale_f32 v28, s[4:5], v3, v3, 1.0
	v_rcp_f32_e32 v29, v28
	v_readlane_b32 s4, v255, 39
	v_readlane_b32 s5, v255, 40
	v_fma_f32 v30, -v28, v29, 1.0
	v_fmac_f32_e32 v29, v30, v29
	v_div_scale_f32 v30, vcc, 1.0, v3, 1.0
	v_mul_f32_e32 v31, v30, v29
	v_fma_f32 v32, -v28, v31, v30
	v_fmac_f32_e32 v31, v32, v29
	v_fma_f32 v28, -v28, v31, v30
	v_lshl_add_u64 v[32:33], s[6:7], 0, v[210:211]
	v_div_fmas_f32 v28, v28, v29, v31
	v_lshlrev_b32_e32 v30, 2, v0
	v_lshl_add_u64 v[34:35], v[32:33], 0, s[16:17]
	v_div_fixup_f32 v3, v28, v3, 1.0
	s_movk_i32 s98, 0x1000
	s_mov_b32 s99, 0
	v_lshl_add_u64 v[52:53], v[34:35], 0, s[98:99]
	s_movk_i32 s98, 0x2000
	v_lshl_add_u64 v[54:55], v[52:53], 0, s[98:99]
	v_lshl_add_u64 v[56:57], v[54:55], 0, s[98:99]
	v_lshl_add_u64 v[58:59], v[56:57], 0, s[98:99]
	global_load_dword v192, v[52:53], off offset:-4096
	global_load_dword v193, v[52:53], off offset:-2048
	global_load_dword v194, v[52:53], off
	global_load_dword v195, v[52:53], off offset:2048
	global_load_dword v196, v[54:55], off offset:-4096
	global_load_dword v197, v[54:55], off offset:-2048
	global_load_dword v198, v[54:55], off
	global_load_dword v199, v[54:55], off offset:2048
	global_load_dword v200, v[56:57], off offset:-4096
	global_load_dword v201, v[56:57], off offset:-2048
	global_load_dword v202, v[56:57], off
	global_load_dword v203, v[56:57], off offset:2048
	global_load_dword v204, v[58:59], off offset:-4096
	global_load_dword v205, v[58:59], off offset:-2048
	global_load_dword v206, v[58:59], off
	global_load_dword v207, v[58:59], off offset:2048
	global_load_dwordx2 v[28:29], v30, s[14:15]
	s_nop 0
	global_load_dwordx2 v[30:31], v30, s[24:25]
	s_nop 0
	s_waitcnt vmcnt(0)
	v_mov_b32_e32 v0, v192
	v_lshlrev_b32_e32 v34, 16, v0
	v_and_b32_e32 v0, 0xffff0000, v0
	v_fmac_f32_e32 v0, 0xba800000, v1
	v_mul_f32_e32 v0, v2, v0
	v_fmac_f32_e32 v34, 0xba800000, v1
	v_fma_f32 v35, v29, v0, v31
	v_lshl_add_u64 v[0:1], v[32:33], 0, s[20:21]
	v_mov_b32_e32 v0, v193
	v_mul_f32_e32 v34, v2, v34
	v_fma_f32 v34, v28, v34, v30
	s_waitcnt vmcnt(0)
	v_lshlrev_b32_e32 v1, 16, v0
	v_and_b32_e32 v0, 0xffff0000, v0
	v_fmac_f32_e32 v1, 0xba800000, v4
	v_fmac_f32_e32 v0, 0xba800000, v4
	v_mul_f32_e32 v1, v5, v1
	v_mul_f32_e32 v0, v5, v0
	v_fma_f32 v2, v28, v1, v30
	v_fma_f32 v40, v29, v0, v31
	v_lshl_add_u64 v[0:1], v[32:33], 0, s[28:29]
	v_mov_b32_e32 v0, v194
	s_waitcnt vmcnt(0)
	v_lshlrev_b32_e32 v1, 16, v0
	v_and_b32_e32 v0, 0xffff0000, v0
	v_fmac_f32_e32 v1, 0xba800000, v6
	v_fmac_f32_e32 v0, 0xba800000, v6
	v_mul_f32_e32 v1, v7, v1
	v_mul_f32_e32 v0, v7, v0
	v_fma_f32 v4, v28, v1, v30
	v_fma_f32 v41, v29, v0, v31
	v_lshl_add_u64 v[0:1], v[32:33], 0, s[30:31]
	v_mov_b32_e32 v0, v195
	s_waitcnt vmcnt(0)
	v_lshlrev_b32_e32 v1, 16, v0
	v_and_b32_e32 v0, 0xffff0000, v0
	v_fmac_f32_e32 v1, 0xba800000, v8
	v_fmac_f32_e32 v0, 0xba800000, v8
	v_mul_f32_e32 v1, v9, v1
	v_mul_f32_e32 v0, v9, v0
	v_fma_f32 v5, v28, v1, v30
	v_fma_f32 v9, v29, v0, v31
	v_lshl_add_u64 v[0:1], v[32:33], 0, s[34:35]
	v_mov_b32_e32 v0, v196
	s_waitcnt vmcnt(0)
; #define LAS __attribute__((address_space(3)))
; __device__ __forceinline__ unsigned cvt_pk_bf16(float lo, float hi) { unsigned r; asm volatile("v_cvt_pk_bf16_f32 %0, %1, %2" : "=v"(r) : "v"(lo), "v"(hi)); return r; }
; __device__ __forceinline__ float bf_lo(unsigned v) { return __uint_as_float(v << 16); }
; __device__ __forceinline__ float bf_hi(unsigned v) { return __uint_as_float(v & 0xffff0000u); }
; __device__ __forceinline__ void sgu_item(int it, const bf16_t* GV, const bf16_t* ZU, const float* sg_, const float* sb_, const float* wsp, const float* bsp, bf16_t* CAT, unsigned char* lds, const int wv) {
;     ...
;         for (int i = 0; i < 16; ++i) { const unsigned v = *(const unsigned*)(GV + (size_t)(tok0 + 16 * wid + i) * 1024 + c0);
;             z0[i] = (bf_lo(v) - mean[i]) * rstd[i] * sgv.x + sbv.x; z1[i] = (bf_hi(v) - mean[i]) * rstd[i] * sgv.y + sbv.y; }
;         u32x4 w0a, w0b, w1a, w1b;
;         w0a.x = cvt_pk_bf16(z0[0], z0[1]); w0a.y = cvt_pk_bf16(z0[2], z0[3]); w0a.z = cvt_pk_bf16(z0[4], z0[5]); w0a.w = cvt_pk_bf16(z0[6], z0[7]);
;         w0b.x = cvt_pk_bf16(z0[8], z0[9]); w0b.y = cvt_pk_bf16(z0[10], z0[11]); w0b.z = cvt_pk_bf16(z0[12], z0[13]); w0b.w = cvt_pk_bf16(z0[14], z0[15]);
;         w1a.x = cvt_pk_bf16(z1[0], z1[1]); w1a.y = cvt_pk_bf16(z1[2], z1[3]); w1a.z = cvt_pk_bf16(z1[4], z1[5]); w1a.w = cvt_pk_bf16(z1[6], z1[7]);
;         w1b.x = cvt_pk_bf16(z1[8], z1[9]); w1b.y = cvt_pk_bf16(z1[10], z1[11]); w1b.z = cvt_pk_bf16(z1[12], z1[13]); w1b.w = cvt_pk_bf16(z1[14], z1[15]);
;         const int x0 = 2 * lane, s0 = (x0 & ~31) + 16 * ((x0 >> 2) & 1) + 4 * ((x0 & 31) >> 3) + (x0 & 3);
;         LAS unsigned char* r0 = ZT + s0 * 272 + 32 * wid;
;         *(LAS u32x4*)(r0) = w0a; *(LAS u32x4*)(r0 + 16) = w0b; *(LAS u32x4*)(r0 + 272) = w1a; *(LAS u32x4*)(r0 + 272 + 16) = w1b;
;     }
;     __syncthreads();
;     const int pl = lane & 15, kg = lane >> 4, p = 16 * wid + pl;
;     bf16x8 Y[4];
; #pragma unroll
;     for (int ks = 0; ks < 4; ++ks) { const float* wp = wsp + ((size_t)g * 128 + p) * 128 + 32 * ks + 8 * kg;
	v_lshlrev_b32_e32 v1, 16, v0
	v_and_b32_e32 v0, 0xffff0000, v0
	v_fmac_f32_e32 v1, 0xba800000, v10
	v_fmac_f32_e32 v0, 0xba800000, v10
	v_mul_f32_e32 v1, v11, v1
	v_mul_f32_e32 v0, v11, v0
	v_fma_f32 v6, v28, v1, v30
	v_fma_f32 v10, v29, v0, v31
	v_lshl_add_u64 v[0:1], v[32:33], 0, s[26:27]
	v_mov_b32_e32 v0, v197
	s_load_dwordx2 s[26:27], s[82:83], 0xa0
	s_waitcnt vmcnt(0)
	v_lshlrev_b32_e32 v1, 16, v0
	v_and_b32_e32 v0, 0xffff0000, v0
	v_fmac_f32_e32 v1, 0xba800000, v12
	v_fmac_f32_e32 v0, 0xba800000, v12
	v_mul_f32_e32 v1, v13, v1
	v_mul_f32_e32 v0, v13, v0
	v_fma_f32 v7, v28, v1, v30
	v_fma_f32 v11, v29, v0, v31
	v_lshl_add_u64 v[0:1], v[32:33], 0, s[36:37]
	v_mov_b32_e32 v0, v198
	s_waitcnt vmcnt(0)
	v_lshlrev_b32_e32 v1, 16, v0
	v_and_b32_e32 v0, 0xffff0000, v0
	v_fmac_f32_e32 v1, 0xba800000, v14
	v_fmac_f32_e32 v0, 0xba800000, v14
	v_mul_f32_e32 v1, v15, v1
	v_mul_f32_e32 v0, v15, v0
	v_fma_f32 v8, v28, v1, v30
	v_fma_f32 v12, v29, v0, v31
	v_lshl_add_u64 v[0:1], v[32:33], 0, s[42:43]
	v_mov_b32_e32 v0, v199
	s_waitcnt vmcnt(0)
	v_lshlrev_b32_e32 v1, 16, v0
	v_and_b32_e32 v0, 0xffff0000, v0
	v_fmac_f32_e32 v1, 0xba800000, v17
	v_fmac_f32_e32 v0, 0xba800000, v17
	v_mul_f32_e32 v1, v18, v1
	v_mul_f32_e32 v0, v18, v0
	v_fma_f32 v13, v28, v1, v30
	v_fma_f32 v14, v29, v0, v31
	v_lshl_add_u64 v[0:1], v[32:33], 0, s[44:45]
	v_mov_b32_e32 v0, v200
	v_readlane_b32 s44, v255, 26
	s_add_i32 s92, s92, s44
	s_waitcnt vmcnt(0)
	v_lshlrev_b32_e32 v1, 16, v0
	v_and_b32_e32 v0, 0xffff0000, v0
	v_fmac_f32_e32 v1, 0xba800000, v19
	v_fmac_f32_e32 v0, 0xba800000, v19
	v_mul_f32_e32 v1, v20, v1
	v_mul_f32_e32 v0, v20, v0
	v_fma_f32 v15, v28, v1, v30
	v_fma_f32 v17, v29, v0, v31
	v_lshl_add_u64 v[0:1], v[32:33], 0, s[10:11]
	v_mov_b32_e32 v0, v201
	s_waitcnt vmcnt(0)
	v_lshlrev_b32_e32 v1, 16, v0
	v_and_b32_e32 v0, 0xffff0000, v0
	v_fmac_f32_e32 v1, 0xba800000, v21
	v_fmac_f32_e32 v0, 0xba800000, v21
	v_mul_f32_e32 v1, v22, v1
	v_mul_f32_e32 v0, v22, v0
	v_fma_f32 v18, v28, v1, v30
	v_fma_f32 v19, v29, v0, v31
	v_lshl_add_u64 v[0:1], v[32:33], 0, s[12:13]
	v_mov_b32_e32 v0, v202
	s_waitcnt vmcnt(0)
	v_lshlrev_b32_e32 v1, 16, v0
	v_and_b32_e32 v0, 0xffff0000, v0
	v_fmac_f32_e32 v1, 0xba800000, v23
	v_fmac_f32_e32 v0, 0xba800000, v23
	v_mul_f32_e32 v1, v24, v1
	v_mul_f32_e32 v0, v24, v0
	v_fma_f32 v20, v28, v1, v30
	v_fma_f32 v21, v29, v0, v31
	v_lshl_add_u64 v[0:1], v[32:33], 0, s[96:97]
	v_mov_b32_e32 v0, v203
	s_waitcnt vmcnt(0)
	v_lshlrev_b32_e32 v1, 16, v0
	v_and_b32_e32 v0, 0xffff0000, v0
	v_fmac_f32_e32 v1, 0xba800000, v25
	v_fmac_f32_e32 v0, 0xba800000, v25
	v_mul_f32_e32 v1, v26, v1
	v_mul_f32_e32 v0, v26, v0
	v_fma_f32 v22, v28, v1, v30
	v_fma_f32 v23, v29, v0, v31
	v_lshl_add_u64 v[0:1], v[32:33], 0, s[94:95]
	v_mov_b32_e32 v0, v204
	s_waitcnt vmcnt(0)
	v_lshlrev_b32_e32 v1, 16, v0
	v_and_b32_e32 v0, 0xffff0000, v0
	v_fmac_f32_e32 v1, 0xba800000, v27
	v_fmac_f32_e32 v0, 0xba800000, v27
	v_mul_f32_e32 v1, v36, v1
	v_mul_f32_e32 v0, v36, v0
	v_fma_f32 v24, v28, v1, v30
	v_fma_f32 v25, v29, v0, v31
	v_lshl_add_u64 v[0:1], v[32:33], 0, s[88:89]
	v_mov_b32_e32 v0, v205
	s_waitcnt vmcnt(0)
	v_lshlrev_b32_e32 v1, 16, v0
	v_and_b32_e32 v0, 0xffff0000, v0
	v_fmac_f32_e32 v1, 0xba800000, v45
	v_fmac_f32_e32 v0, 0xba800000, v45
	v_mul_f32_e32 v1, v37, v1
	v_mul_f32_e32 v0, v37, v0
	v_fma_f32 v26, v28, v1, v30
	v_fma_f32 v27, v29, v0, v31
	v_lshl_add_u64 v[0:1], v[32:33], 0, s[86:87]
	v_mov_b32_e32 v0, v206
	s_waitcnt vmcnt(0)
	v_lshlrev_b32_e32 v1, 16, v0
	v_and_b32_e32 v0, 0xffff0000, v0
	v_fmac_f32_e32 v1, 0xba800000, v47
	v_fmac_f32_e32 v0, 0xba800000, v47
	v_mul_f32_e32 v1, v38, v1
	v_mul_f32_e32 v0, v38, v0
	v_fma_f32 v36, v28, v1, v30
	v_fma_f32 v37, v29, v0, v31
	v_lshl_add_u64 v[0:1], v[32:33], 0, s[22:23]
	v_mov_b32_e32 v0, v207
	s_waitcnt vmcnt(0)
	v_lshlrev_b32_e32 v1, 16, v0
	v_and_b32_e32 v0, 0xffff0000, v0
	v_fmac_f32_e32 v1, 0xba800000, v48
	v_fmac_f32_e32 v0, 0xba800000, v48
	v_mul_f32_e32 v1, v3, v1
	v_mul_f32_e32 v0, v3, v0
	v_fma_f32 v28, v28, v1, v30
	v_fmac_f32_e32 v31, v29, v0
	v_cvt_pk_bf16_f32 v0, v34, v2
	v_cvt_pk_bf16_f32 v1, v4, v5
	v_cvt_pk_bf16_f32 v2, v6, v7
	v_cvt_pk_bf16_f32 v3, v8, v13
	v_cvt_pk_bf16_f32 v4, v15, v18
	v_cvt_pk_bf16_f32 v5, v20, v22
	v_cvt_pk_bf16_f32 v6, v24, v26
	v_cvt_pk_bf16_f32 v7, v36, v28
	v_cvt_pk_bf16_f32 v8, v35, v40
	v_cvt_pk_bf16_f32 v9, v41, v9
	v_cvt_pk_bf16_f32 v10, v10, v11
	v_cvt_pk_bf16_f32 v11, v12, v14
	v_cvt_pk_bf16_f32 v12, v17, v19
	v_lshlrev_b32_e32 v17, 3, v16
	v_and_b32_e32 v17, 16, v17
	v_and_b32_e32 v18, 12, v16
	v_and_b32_e32 v19, 0x62, v39
	v_or3_b32 v17, v18, v17, v19
	v_mov_b32_e32 v18, s1
	s_movk_i32 s1, 0x110
	v_cvt_pk_bf16_f32 v13, v21, v23
	v_cvt_pk_bf16_f32 v14, v25, v27
	v_mad_u32_u24 v17, v17, s1, v18
	v_cvt_pk_bf16_f32 v15, v37, v31
	ds_write_b128 v17, v[0:3]
	ds_write_b128 v17, v[4:7] offset:16
	ds_write_b128 v17, v[8:11] offset:272
	ds_write_b128 v17, v[12:15] offset:288
	v_and_b32_e32 v14, 15, v16
	v_lshl_or_b32 v44, s9, 4, v14
	v_ashrrev_i32_e32 v45, 31, v44
	v_lshl_add_u64 v[0:1], v[44:45], 0, s[38:39]
	v_lshrrev_b32_e32 v2, 1, v16
	v_lshlrev_b64 v[0:1], 9, v[0:1]
	v_and_b32_e32 v45, 24, v2
	v_lshl_add_u64 v[0:1], s[40:41], 0, v[0:1]
	v_lshlrev_b32_e32 v210, 2, v45
	v_lshl_add_u64 v[12:13], v[0:1], 0, v[210:211]
	s_waitcnt lgkmcnt(0)
	s_barrier
; #define LAS __attribute__((address_space(3)))
; __device__ __forceinline__ unsigned cvt_pk_bf16(float lo, float hi) { unsigned r; asm volatile("v_cvt_pk_bf16_f32 %0, %1, %2" : "=v"(r) : "v"(lo), "v"(hi)); return r; }
; __device__ __forceinline__ void sgu_item(int it, const bf16_t* GV, const bf16_t* ZU, const float* sg_, const float* sb_, const float* wsp, const float* bsp, bf16_t* CAT, unsigned char* lds, const int wv) {
;     ...
;     for (int ks = 0; ks < 4; ++ks) { const float* wp = wsp + ((size_t)g * 128 + p) * 128 + 32 * ks + 8 * kg;
;         const f32x4 a = *(const f32x4*)wp, c = *(const f32x4*)(wp + 4);
;         u32x4 w; w.x = cvt_pk_bf16(a[0], a[1]); w.y = cvt_pk_bf16(a[2], a[3]); w.z = cvt_pk_bf16(c[0], c[1]); w.w = cvt_pk_bf16(c[2], c[3]);
;         Y[ks] = *reinterpret_cast<bf16x8*>(&w); }
;     f32x4 acc[8];
; #pragma unroll
;     for (int ct = 0; ct < 8; ++ct) { acc[ct] = (f32x4){0.f, 0.f, 0.f, 0.f};
; #pragma unroll
;         for (int ks = 0; ks < 4; ++ks) { const bf16x8 X = *(const LAS bf16x8*)(ZT + (16 * ct + pl) * 272 + 64 * ks + 16 * kg);
;             acc[ct] = __builtin_amdgcn_mfma_f32_16x16x32_bf16(X, Y[ks], acc[ct], 0, 0, 0); } }
	global_load_dwordx4 v[64:67], v[12:13], off offset:16
	global_load_dwordx4 v[68:71], v[12:13], off
	global_load_dwordx4 v[72:75], v[12:13], off offset:144
	global_load_dwordx4 v[76:79], v[12:13], off offset:128
	global_load_dwordx4 v[80:83], v[12:13], off offset:272
	global_load_dwordx4 v[84:87], v[12:13], off offset:256
	global_load_dwordx4 v[88:91], v[12:13], off offset:400
	global_load_dwordx4 v[92:95], v[12:13], off offset:384
	s_waitcnt vmcnt(0)
	v_cvt_pk_bf16_f32 v4, v68, v69
	v_cvt_pk_bf16_f32 v5, v70, v71
	v_cvt_pk_bf16_f32 v6, v64, v65
	v_cvt_pk_bf16_f32 v7, v66, v67
	v_cvt_pk_bf16_f32 v32, v76, v77
	v_cvt_pk_bf16_f32 v33, v78, v79
	v_cvt_pk_bf16_f32 v34, v72, v73
	v_cvt_pk_bf16_f32 v35, v74, v75
	v_cvt_pk_bf16_f32 v36, v84, v85
	v_cvt_pk_bf16_f32 v37, v86, v87
	v_cvt_pk_bf16_f32 v38, v80, v81
	v_cvt_pk_bf16_f32 v39, v82, v83
	v_cvt_pk_bf16_f32 v40, v92, v93
	v_cvt_pk_bf16_f32 v41, v94, v95
	v_cvt_pk_bf16_f32 v42, v88, v89
	v_cvt_pk_bf16_f32 v43, v90, v91
	v_and_b32_e32 v0, 48, v16
	v_mul_u32_u24_e32 v1, 0x110, v14
	v_add3_u32 v46, 0, v0, v1
	ds_read_b128 v[0:3], v46
	ds_read_b128 v[8:11], v46 offset:64
	s_waitcnt lgkmcnt(1)
	v_mfma_f32_16x16x32_bf16 v[0:3], v[0:3], v[4:7], 0
	ds_read_b128 v[12:15], v46 offset:21824
	ds_read_b128 v[48:51], v46 offset:26176
	s_and_b32 s1, s85, 0xffffff80
	s_waitcnt lgkmcnt(2)
	v_mfma_f32_16x16x32_bf16 v[0:3], v[8:11], v[32:35], v[0:3]
	ds_read_b128 v[8:11], v46 offset:128
	s_add_i32 s85, s85, s52
	s_cmpk_gt_i32 s92, 0x3ff
	s_waitcnt lgkmcnt(0)
	v_mfma_f32_16x16x32_bf16 v[0:3], v[8:11], v[36:39], v[0:3]
	ds_read_b128 v[8:11], v46 offset:192
	s_waitcnt lgkmcnt(0)
	v_mfma_f32_16x16x32_bf16 v[24:27], v[8:11], v[40:43], v[0:3]
	s_nop 4
	ds_read_b128 v[0:3], v46 offset:4352
	ds_read_b128 v[8:11], v46 offset:4416
	s_waitcnt lgkmcnt(1)
	v_mfma_f32_16x16x32_bf16 v[0:3], v[0:3], v[4:7], 0
	s_waitcnt lgkmcnt(0)
	v_mfma_f32_16x16x32_bf16 v[0:3], v[8:11], v[32:35], v[0:3]
	ds_read_b128 v[8:11], v46 offset:4480
	s_waitcnt lgkmcnt(0)
	v_mfma_f32_16x16x32_bf16 v[0:3], v[8:11], v[36:39], v[0:3]
	ds_read_b128 v[8:11], v46 offset:4544
	s_waitcnt lgkmcnt(0)
	v_mfma_f32_16x16x32_bf16 v[28:31], v[8:11], v[40:43], v[0:3]
	s_nop 4
	ds_read_b128 v[0:3], v46 offset:8704
	ds_read_b128 v[8:11], v46 offset:8768
	s_waitcnt lgkmcnt(1)
	v_mfma_f32_16x16x32_bf16 v[0:3], v[0:3], v[4:7], 0
	s_waitcnt lgkmcnt(0)
	v_mfma_f32_16x16x32_bf16 v[0:3], v[8:11], v[32:35], v[0:3]
	ds_read_b128 v[8:11], v46 offset:8832
	s_waitcnt lgkmcnt(0)
	v_mfma_f32_16x16x32_bf16 v[0:3], v[8:11], v[36:39], v[0:3]
	ds_read_b128 v[8:11], v46 offset:8896
	s_waitcnt lgkmcnt(0)
	v_mfma_f32_16x16x32_bf16 v[16:19], v[8:11], v[40:43], v[0:3]
	s_nop 4
	ds_read_b128 v[0:3], v46 offset:13056
	ds_read_b128 v[8:11], v46 offset:13120
	s_waitcnt lgkmcnt(1)
	v_mfma_f32_16x16x32_bf16 v[0:3], v[0:3], v[4:7], 0
	s_waitcnt lgkmcnt(0)
	v_mfma_f32_16x16x32_bf16 v[0:3], v[8:11], v[32:35], v[0:3]
	ds_read_b128 v[8:11], v46 offset:13184
	s_waitcnt lgkmcnt(0)
	v_mfma_f32_16x16x32_bf16 v[0:3], v[8:11], v[36:39], v[0:3]
	ds_read_b128 v[8:11], v46 offset:13248
	s_waitcnt lgkmcnt(0)
	v_mfma_f32_16x16x32_bf16 v[20:23], v[8:11], v[40:43], v[0:3]
	s_nop 4
	ds_read_b128 v[0:3], v46 offset:17408
	ds_read_b128 v[8:11], v46 offset:17472
	s_waitcnt lgkmcnt(1)
	v_mfma_f32_16x16x32_bf16 v[0:3], v[0:3], v[4:7], 0
	s_waitcnt lgkmcnt(0)
	v_mfma_f32_16x16x32_bf16 v[0:3], v[8:11], v[32:35], v[0:3]
	ds_read_b128 v[8:11], v46 offset:17536
	s_waitcnt lgkmcnt(0)
	v_mfma_f32_16x16x32_bf16 v[0:3], v[8:11], v[36:39], v[0:3]
	ds_read_b128 v[8:11], v46 offset:17600
	s_waitcnt lgkmcnt(0)
	v_mfma_f32_16x16x32_bf16 v[8:11], v[8:11], v[40:43], v[0:3]
	s_nop 4
	ds_read_b128 v[0:3], v46 offset:21760
	s_waitcnt lgkmcnt(0)
	v_mfma_f32_16x16x32_bf16 v[0:3], v[0:3], v[4:7], 0
	v_mfma_f32_16x16x32_bf16 v[0:3], v[12:15], v[32:35], v[0:3]
	ds_read_b128 v[12:15], v46 offset:21888
	s_waitcnt lgkmcnt(0)
	v_mfma_f32_16x16x32_bf16 v[0:3], v[12:15], v[36:39], v[0:3]
	ds_read_b128 v[12:15], v46 offset:21952
	s_waitcnt lgkmcnt(0)
	v_mfma_f32_16x16x32_bf16 v[12:15], v[12:15], v[40:43], v[0:3]
	s_nop 4
	ds_read_b128 v[0:3], v46 offset:26112
	s_waitcnt lgkmcnt(0)
	v_mfma_f32_16x16x32_bf16 v[0:3], v[0:3], v[4:7], 0
	v_mfma_f32_16x16x32_bf16 v[0:3], v[48:51], v[32:35], v[0:3]
	ds_read_b128 v[48:51], v46 offset:26240
	s_waitcnt lgkmcnt(0)
	v_mfma_f32_16x16x32_bf16 v[0:3], v[48:51], v[36:39], v[0:3]
	ds_read_b128 v[48:51], v46 offset:26304
	s_waitcnt lgkmcnt(0)
	v_mfma_f32_16x16x32_bf16 v[0:3], v[48:51], v[40:43], v[0:3]
	ds_read_b128 v[48:51], v46 offset:30464
	s_waitcnt lgkmcnt(0)
	v_mfma_f32_16x16x32_bf16 v[4:7], v[48:51], v[4:7], 0
	ds_read_b128 v[48:51], v46 offset:30528
	s_waitcnt lgkmcnt(0)
	v_mfma_f32_16x16x32_bf16 v[4:7], v[48:51], v[32:35], v[4:7]
	ds_read_b128 v[32:35], v46 offset:30592
	s_waitcnt lgkmcnt(0)
	v_mfma_f32_16x16x32_bf16 v[4:7], v[32:35], v[36:39], v[4:7]
	ds_read_b128 v[32:35], v46 offset:30656
	s_waitcnt lgkmcnt(0)
; __device__ __forceinline__ unsigned cvt_pk_bf16(float lo, float hi) { unsigned r; asm volatile("v_cvt_pk_bf16_f32 %0, %1, %2" : "=v"(r) : "v"(lo), "v"(hi)); return r; }
; __device__ __forceinline__ float bf_lo(unsigned v) { return __uint_as_float(v << 16); }
; __device__ __forceinline__ float bf_hi(unsigned v) { return __uint_as_float(v & 0xffff0000u); }
; __device__ __forceinline__ void sgu_item(int it, const bf16_t* GV, const bf16_t* ZU, const float* sg_, const float* sb_, const float* wsp, const float* bsp, bf16_t* CAT, unsigned char* lds, const int wv) {
;     ...
;             acc[ct] = __builtin_amdgcn_mfma_f32_16x16x32_bf16(X, Y[ks], acc[ct], 0, 0, 0); } }
;     const float bs = bsp[g * 128 + p]; const size_t tok = (size_t)(tok0 + p);
; #pragma unroll
;     for (int j = 0; j < 4; ++j) { const int c = g * 128 + 32 * j + 8 * kg;
;         const u32x4 zu = *(const u32x4*)(ZU + tok * 1024 + c);
;         const f32x4 e0 = acc[2 * j] + bs, e1 = acc[2 * j + 1] + bs;
;         u32x4 w; w.x = cvt_pk_bf16(bf_lo(zu.x) * e0[0], bf_hi(zu.x) * e0[1]); w.y = cvt_pk_bf16(bf_lo(zu.y) * e0[2], bf_hi(zu.y) * e0[3]);
;         w.z = cvt_pk_bf16(bf_lo(zu.z) * e1[0], bf_hi(zu.z) * e1[1]); w.w = cvt_pk_bf16(bf_lo(zu.w) * e1[2], bf_hi(zu.w) * e1[3]);
;         *(u32x4*)(CAT + tok * DM + 1024 + c) = w; }
	v_mfma_f32_16x16x32_bf16 v[4:7], v[32:35], v[40:43], v[4:7]
	v_add_u32_e32 v32, s38, v44
	v_ashrrev_i32_e32 v33, 31, v32
	v_add_u32_e32 v34, s1, v44
	v_lshl_add_u64 v[32:33], v[32:33], 2, s[18:19]
	v_ashrrev_i32_e32 v35, 31, v34
	global_load_dword v32, v[32:33], off
	v_or_b32_e32 v33, s38, v45
	v_lshlrev_b64 v[36:37], 11, v[34:35]
	v_lshl_add_u64 v[36:37], s[4:5], 0, v[36:37]
	v_lshlrev_b32_e32 v210, 1, v33
	v_lshl_add_u64 v[36:37], v[36:37], 0, v[210:211]
	global_load_dwordx4 v[38:41], v[36:37], off
	global_load_dwordx4 v[96:99], v[36:37], off offset:64
	global_load_dwordx4 v[100:103], v[36:37], off offset:128
	global_load_dwordx4 v[104:107], v[36:37], off offset:192
	v_lshlrev_b64 v[34:35], 12, v[34:35]
	v_lshl_add_u64 v[34:35], s[26:27], 0, v[34:35]
	s_mov_b64 s[4:5], 0x21800800
	v_lshl_add_u64 v[34:35], v[34:35], 0, s[4:5]
	s_waitcnt vmcnt(4)
	v_pk_add_f32 v[26:27], v[26:27], v[32:33] op_sel_hi:[1,0]
	v_pk_add_f32 v[24:25], v[24:25], v[32:33] op_sel_hi:[1,0]
	v_pk_add_f32 v[30:31], v[30:31], v[32:33] op_sel_hi:[1,0]
	v_pk_add_f32 v[28:29], v[28:29], v[32:33] op_sel_hi:[1,0]
	s_waitcnt vmcnt(0)
	v_lshlrev_b32_e32 v33, 16, v38
	v_mul_f32_e32 v24, v24, v33
	v_and_b32_e32 v33, 0xffff0000, v38
	v_mul_f32_e32 v25, v25, v33
	v_cvt_pk_bf16_f32 v24, v24, v25
	v_lshlrev_b32_e32 v25, 16, v39
	v_mul_f32_e32 v25, v26, v25
	v_and_b32_e32 v26, 0xffff0000, v39
	v_mul_f32_e32 v26, v27, v26
	v_cvt_pk_bf16_f32 v25, v25, v26
	v_lshlrev_b32_e32 v26, 16, v40
	v_and_b32_e32 v27, 0xffff0000, v40
	v_mul_f32_e32 v26, v28, v26
	v_mul_f32_e32 v27, v29, v27
	v_cvt_pk_bf16_f32 v26, v26, v27
	v_lshlrev_b32_e32 v27, 16, v41
	v_and_b32_e32 v28, 0xffff0000, v41
	v_mul_f32_e32 v27, v30, v27
	v_mul_f32_e32 v28, v31, v28
	v_cvt_pk_bf16_f32 v27, v27, v28
	v_lshl_add_u64 v[28:29], v[34:35], 0, v[210:211]
	global_store_dwordx4 v[28:29], v[24:27], off
	s_nop 1
	v_mov_b32_e32 v24, v96
	v_mov_b32_e32 v25, v97
	v_mov_b32_e32 v26, v98
	v_mov_b32_e32 v27, v99
	v_pk_add_f32 v[16:17], v[16:17], v[32:33] op_sel_hi:[1,0]
	v_pk_add_f32 v[18:19], v[18:19], v[32:33] op_sel_hi:[1,0]
	v_pk_add_f32 v[20:21], v[20:21], v[32:33] op_sel_hi:[1,0]
	v_pk_add_f32 v[22:23], v[22:23], v[32:33] op_sel_hi:[1,0]
	v_pk_add_f32 v[8:9], v[8:9], v[32:33] op_sel_hi:[1,0]
	v_pk_add_f32 v[10:11], v[10:11], v[32:33] op_sel_hi:[1,0]
	v_pk_add_f32 v[12:13], v[12:13], v[32:33] op_sel_hi:[1,0]
	v_pk_add_f32 v[14:15], v[14:15], v[32:33] op_sel_hi:[1,0]
	v_pk_add_f32 v[0:1], v[0:1], v[32:33] op_sel_hi:[1,0]
	v_pk_add_f32 v[2:3], v[2:3], v[32:33] op_sel_hi:[1,0]
	v_pk_add_f32 v[4:5], v[4:5], v[32:33] op_sel_hi:[1,0]
	v_pk_add_f32 v[6:7], v[6:7], v[32:33] op_sel_hi:[1,0]
	v_lshlrev_b32_e32 v28, 16, v24
	v_and_b32_e32 v24, 0xffff0000, v24
	v_mul_f32_e32 v16, v16, v28
	v_mul_f32_e32 v17, v17, v24
	v_cvt_pk_bf16_f32 v16, v16, v17
	v_lshlrev_b32_e32 v17, 16, v25
	v_mul_f32_e32 v17, v18, v17
	v_and_b32_e32 v18, 0xffff0000, v25
	v_mul_f32_e32 v18, v19, v18
	v_cvt_pk_bf16_f32 v17, v17, v18
	v_lshlrev_b32_e32 v18, 16, v26
	v_and_b32_e32 v19, 0xffff0000, v26
	v_mul_f32_e32 v18, v20, v18
	v_mul_f32_e32 v19, v21, v19
	v_cvt_pk_bf16_f32 v18, v18, v19
	v_lshlrev_b32_e32 v19, 16, v27
	v_and_b32_e32 v20, 0xffff0000, v27
	v_mul_f32_e32 v19, v22, v19
	v_mul_f32_e32 v20, v23, v20
	v_cvt_pk_bf16_f32 v19, v19, v20
	v_or_b32_e32 v20, 64, v210
	v_mov_b32_e32 v21, v211
	v_lshl_add_u64 v[20:21], v[34:35], 0, v[20:21]
	global_store_dwordx4 v[20:21], v[16:19], off
	s_nop 1
	v_mov_b32_e32 v16, v100
	v_mov_b32_e32 v17, v101
	v_mov_b32_e32 v18, v102
	v_mov_b32_e32 v19, v103
	v_lshlrev_b32_e32 v20, 16, v16
	v_and_b32_e32 v16, 0xffff0000, v16
	v_mul_f32_e32 v8, v8, v20
	v_mul_f32_e32 v9, v9, v16
	v_cvt_pk_bf16_f32 v8, v8, v9
	v_lshlrev_b32_e32 v9, 16, v17
	v_mul_f32_e32 v9, v10, v9
	v_and_b32_e32 v10, 0xffff0000, v17
	v_mul_f32_e32 v10, v11, v10
	v_cvt_pk_bf16_f32 v9, v9, v10
	v_lshlrev_b32_e32 v10, 16, v18
	v_and_b32_e32 v11, 0xffff0000, v18
	v_mul_f32_e32 v10, v12, v10
	v_mul_f32_e32 v11, v13, v11
	v_cvt_pk_bf16_f32 v10, v10, v11
	v_lshlrev_b32_e32 v11, 16, v19
	v_and_b32_e32 v12, 0xffff0000, v19
	v_mul_f32_e32 v11, v14, v11
	v_mul_f32_e32 v12, v15, v12
	v_cvt_pk_bf16_f32 v11, v11, v12
	v_or_b32_e32 v12, 0x80, v210
	v_mov_b32_e32 v13, v211
	v_lshl_add_u64 v[12:13], v[34:35], 0, v[12:13]
	global_store_dwordx4 v[12:13], v[8:11], off
	s_nop 1
	v_mov_b32_e32 v8, v104
	v_mov_b32_e32 v9, v105
	v_mov_b32_e32 v10, v106
	v_mov_b32_e32 v11, v107
	v_or_b32_e32 v210, 0xc0, v210
	v_lshlrev_b32_e32 v12, 16, v8
	v_and_b32_e32 v8, 0xffff0000, v8
	v_mul_f32_e32 v0, v0, v12
	v_mul_f32_e32 v1, v1, v8
	v_cvt_pk_bf16_f32 v0, v0, v1
	v_lshlrev_b32_e32 v1, 16, v9
	v_mul_f32_e32 v1, v2, v1
	v_and_b32_e32 v2, 0xffff0000, v9
	v_mul_f32_e32 v2, v3, v2
	v_cvt_pk_bf16_f32 v1, v1, v2
	v_lshlrev_b32_e32 v2, 16, v10
	v_and_b32_e32 v3, 0xffff0000, v10
	v_mul_f32_e32 v2, v4, v2
	v_mul_f32_e32 v3, v5, v3
	v_cvt_pk_bf16_f32 v2, v2, v3
	v_lshlrev_b32_e32 v3, 16, v11
	v_and_b32_e32 v4, 0xffff0000, v11
	v_mul_f32_e32 v3, v6, v3
	v_mul_f32_e32 v4, v7, v4
	v_cvt_pk_bf16_f32 v3, v3, v4
	v_lshl_add_u64 v[4:5], v[34:35], 0, v[210:211]
	global_store_dwordx4 v[4:5], v[0:3], off
	s_cbranch_scc0 .LBB0_288
